# nt (streaming) loads for the read-once residual stream in the three RMSNorm phases, on top of q7
# baseline (speedup 1.0000x reference)
; template <int NR>
; __device__ __forceinline__ void rms_rows_bf16(const float* x, const float* g, bf16* o, int m0, int mstride, int lane) {
;     { size_t z = 0; asm volatile("" : "+s"(z)); g += z; }
;     const f32x4* gr = (const f32x4*)g + lane;
;     f32x4 v[NR][4];
; #pragma unroll
;     for (int k = 0; k < NR; ++k) { const f32x4* xr = (const f32x4*)(x + (size_t)(m0 + k * mstride) * DM) + lane;
; #pragma unroll
;         for (int j = 0; j < 4; ++j) v[k][j] = xr[64 * j]; }
;     f32x4 gg[4];
; #pragma unroll
;     for (int j = 0; j < 4; ++j) gg[j] = gr[64 * j];
; #pragma unroll
;     for (int k = 0; k < NR; ++k) { float s = 0.f;
; #pragma unroll
;         for (int j = 0; j < 4; ++j) s += (v[k][j].x * v[k][j].x + v[k][j].y * v[k][j].y) + (v[k][j].z * v[k][j].z + v[k][j].w * v[k][j].w);
;         const float rs = __builtin_amdgcn_rsqf(wave_sum(s) * (1.f / DM) + 1e-6f);
.LBB0_58:
	s_ashr_i32 s39, s38, 31
	s_lshl_b64 s[20:21], s[38:39], 12
	s_mov_b64 s[52:53], 0
	v_lshl_add_u64 v[0:1], v[84:85], 0, s[20:21]
	global_load_dwordx4 v[72:75], v[0:1], off nt
	global_load_dwordx4 v[60:63], v[0:1], off offset:1024 nt
	global_load_dwordx4 v[40:43], v[0:1], off offset:3072 nt
	global_load_dwordx4 v[52:55], v[0:1], off offset:2048 nt
	s_add_i32 s50, s38, s76
	s_ashr_i32 s51, s50, 31
	s_lshl_b64 s[20:21], s[50:51], 12
	v_lshl_add_u64 v[0:1], v[84:85], 0, s[20:21]
	global_load_dwordx4 v[24:27], v[0:1], off nt
	global_load_dwordx4 v[20:23], v[0:1], off offset:1024 nt
	global_load_dwordx4 v[16:19], v[0:1], off offset:3072 nt
	global_load_dwordx4 v[76:79], v[0:1], off offset:2048 nt
	v_and_b32_e32 v2, 64, v228
	v_xor_b32_e32 v3, 1, v228
	v_add_u32_e32 v2, 64, v2
	v_xor_b32_e32 v4, 2, v228
	v_cmp_lt_i32_e32 vcc, v3, v2
	v_xor_b32_e32 v5, 4, v228
	v_xor_b32_e32 v6, 8, v228
	v_cndmask_b32_e32 v32, v228, v3, vcc
	v_cmp_lt_i32_e32 vcc, v4, v2
	v_xor_b32_e32 v7, 16, v228
	v_xor_b32_e32 v8, 32, v228
	v_cndmask_b32_e32 v33, v228, v4, vcc
	v_cmp_lt_i32_e32 vcc, v5, v2
	v_lshl_add_u64 v[0:1], s[52:53], 2, v[86:87]
	v_lshlrev_b32_e32 v92, 2, v32
	v_cndmask_b32_e32 v34, v228, v5, vcc
	v_cmp_lt_i32_e32 vcc, v6, v2
	v_lshlrev_b32_e32 v95, 2, v33
	v_lshlrev_b32_e32 v94, 2, v34
	v_cndmask_b32_e32 v35, v228, v6, vcc
	v_cmp_lt_i32_e32 vcc, v7, v2
	v_lshlrev_b32_e32 v93, 2, v35
	s_add_i32 s48, s4, s38
	v_cndmask_b32_e32 v36, v228, v7, vcc
	v_cmp_lt_i32_e32 vcc, v8, v2
	v_lshlrev_b32_e32 v83, 2, v36
	s_ashr_i32 s49, s48, 31
	v_cndmask_b32_e32 v37, v228, v8, vcc
	global_load_dwordx4 v[12:15], v[0:1], off nt
	global_load_dwordx4 v[8:11], v[0:1], off offset:1024 nt
	global_load_dwordx4 v[4:7], v[0:1], off offset:2048 nt
	s_nop 0
	global_load_dwordx4 v[0:3], v[0:1], off offset:3072 nt
	v_lshlrev_b32_e32 v81, 2, v37
	s_lshl_b64 s[22:23], s[48:49], 12
	v_lshl_add_u64 v[28:29], v[84:85], 0, s[22:23]
	global_load_dwordx4 v[68:71], v[28:29], off nt
	global_load_dwordx4 v[56:59], v[28:29], off offset:1024 nt
	s_add_i32 s42, s34, s38
	s_ashr_i32 s43, s42, 31
	s_lshl_b64 s[24:25], s[42:43], 12
	v_lshl_add_u64 v[30:31], v[84:85], 0, s[24:25]
	s_lshl_b64 s[20:21], s[38:39], 11
	v_lshl_add_u64 v[90:91], v[88:89], 0, s[20:21]
	s_lshl_b64 s[20:21], s[50:51], 11
	s_add_i32 s19, s50, s76
	s_add_i32 s19, s19, s76
	s_add_i32 s38, s19, s76
	s_add_i32 s19, s34, s38
	s_waitcnt vmcnt(13)
	v_pk_mul_f32 v[32:33], v[74:75], v[74:75]
	v_pk_mul_f32 v[34:35], v[72:73], v[72:73]
	s_waitcnt vmcnt(12)
	v_pk_mul_f32 v[36:37], v[62:63], v[62:63]
	v_pk_mul_f32 v[38:39], v[60:61], v[60:61]
	v_pk_mov_b32 v[48:49], v[34:35], v[32:33] op_sel:[1,0]
	v_mov_b32_e32 v35, v33
	v_pk_mov_b32 v[32:33], v[38:39], v[36:37] op_sel:[1,0]
	v_mov_b32_e32 v39, v37
	s_waitcnt vmcnt(11)
	v_mul_f32_e32 v47, v40, v40
	s_waitcnt vmcnt(10)
	v_mul_f32_e32 v44, v53, v53
	v_mul_f32_e32 v46, v55, v55
	v_pk_add_f32 v[34:35], v[48:49], v[34:35]
	v_pk_add_f32 v[32:33], v[32:33], v[38:39]
	v_mul_f32_e32 v50, v41, v41
	v_mul_f32_e32 v51, v42, v42
	v_mul_f32_e32 v64, v43, v43
	v_pk_fma_f32 v[36:37], v[52:53], v[52:53], v[44:45] op_sel_hi:[1,1,0]
	v_pk_fma_f32 v[44:45], v[54:55], v[54:55], v[46:47] op_sel_hi:[1,1,0]
	v_pk_add_f32 v[34:35], v[34:35], v[34:35] op_sel:[0,1] op_sel_hi:[1,0]
	v_pk_add_f32 v[32:33], v[32:33], v[32:33] op_sel:[0,1] op_sel_hi:[1,0]
	v_mov_b32_e32 v37, v51
	v_mov_b32_e32 v45, v64
	v_mov_b32_e32 v35, v47
	v_mov_b32_e32 v33, v50
	v_pk_add_f32 v[36:37], v[36:37], v[44:45]
	v_pk_add_f32 v[32:33], v[34:35], v[32:33]
	s_waitcnt vmcnt(9)
	v_pk_mul_f32 v[96:97], v[26:27], v[26:27]
	v_pk_add_f32 v[32:33], v[32:33], v[36:37]
	global_load_dwordx4 v[64:67], v[28:29], off offset:2048 nt
	global_load_dwordx4 v[48:51], v[28:29], off offset:3072 nt
	global_load_dwordx4 v[44:47], v[30:31], off nt
	global_load_dwordx4 v[36:39], v[30:31], off offset:1024 nt
	v_add_f32_e32 v32, v32, v33
	ds_bpermute_b32 v33, v92, v32
	v_pk_mul_f32 v[98:99], v[24:25], v[24:25]
	s_waitcnt vmcnt(12)
	v_pk_mul_f32 v[100:101], v[22:23], v[22:23]
	v_pk_mov_b32 v[106:107], v[98:99], v[96:97] op_sel:[1,0]
	v_mov_b32_e32 v99, v97
	s_waitcnt lgkmcnt(0)
	v_add_f32_e32 v102, v32, v33
	ds_bpermute_b32 v103, v95, v102
	v_pk_add_f32 v[98:99], v[106:107], v[98:99]
	s_waitcnt vmcnt(11)
	v_mul_f32_e32 v108, v16, v16
	v_mul_f32_e32 v109, v17, v17
	v_pk_add_f32 v[98:99], v[98:99], v[98:99] op_sel:[0,1] op_sel_hi:[1,0]
	s_waitcnt lgkmcnt(0)
	v_add_f32_e32 v104, v102, v103
	ds_bpermute_b32 v105, v94, v104
	v_pk_mul_f32 v[102:103], v[20:21], v[20:21]
	v_mov_b32_e32 v99, v108
	v_pk_mov_b32 v[96:97], v[102:103], v[100:101] op_sel:[1,0]
	v_mov_b32_e32 v103, v101
	s_waitcnt lgkmcnt(0)
	v_add_f32_e32 v105, v104, v105
	ds_bpermute_b32 v111, v93, v105
	s_waitcnt vmcnt(10)
	v_mul_f32_e32 v104, v77, v77
	v_pk_add_f32 v[96:97], v[96:97], v[102:103]
	v_mul_f32_e32 v110, v18, v18
	v_pk_add_f32 v[96:97], v[96:97], v[96:97] op_sel:[0,1] op_sel_hi:[1,0]
	s_waitcnt lgkmcnt(0)
	v_add_f32_e32 v105, v105, v111
	ds_bpermute_b32 v111, v83, v105
	v_pk_fma_f32 v[100:101], v[76:77], v[76:77], v[104:105] op_sel_hi:[1,1,0]
	v_mul_f32_e32 v112, v19, v19
	v_mov_b32_e32 v101, v110
	global_load_dwordx4 v[32:35], v[30:31], off offset:2048 nt
	s_nop 0
	global_load_dwordx4 v[28:31], v[30:31], off offset:3072 nt
	s_waitcnt lgkmcnt(0)
	v_add_f32_e32 v104, v105, v111
	ds_bpermute_b32 v105, v81, v104
	s_waitcnt lgkmcnt(0)
	v_add_f32_e32 v97, v104, v105
	v_fmamk_f32 v97, v97, 0x3a800000, v230
	v_rsq_f32_e32 v102, v97
	v_mov_b32_e32 v97, v109
	v_pk_add_f32 v[96:97], v[98:99], v[96:97]
	v_mul_f32_e32 v98, v79, v79
	v_pk_fma_f32 v[98:99], v[78:79], v[78:79], v[98:99] op_sel_hi:[1,1,0]
	v_pk_mul_f32 v[72:73], v[72:73], v[102:103] op_sel_hi:[1,0]
	v_mov_b32_e32 v99, v112
	v_pk_add_f32 v[98:99], v[100:101], v[98:99]
	v_pk_mul_f32 v[74:75], v[74:75], v[102:103] op_sel_hi:[1,0]
	v_pk_add_f32 v[96:97], v[96:97], v[98:99]
	s_waitcnt vmcnt(11)
; __device__ __forceinline__ unsigned pk2(float lo, float hi) { f32x2_t v = {lo, hi}; bf16x2_t b = __builtin_convertvector(v, bf16x2_t); return __builtin_bit_cast(unsigned, b); }
; template <int NR>
; __device__ __forceinline__ void rms_rows_bf16(const float* x, const float* g, bf16* o, int m0, int mstride, int lane) {
;     ...
;     for (int k = 0; k < NR; ++k) { float s = 0.f;
; #pragma unroll
;         for (int j = 0; j < 4; ++j) s += (v[k][j].x * v[k][j].x + v[k][j].y * v[k][j].y) + (v[k][j].z * v[k][j].z + v[k][j].w * v[k][j].w);
;         const float rs = __builtin_amdgcn_rsqf(wave_sum(s) * (1.f / DM) + 1e-6f);
;         v2u* o8 = (v2u*)(o + (size_t)(m0 + k * mstride) * DM) + lane;
; #pragma unroll
;         for (int j = 0; j < 4; ++j) { v2u w; w.x = pk2(v[k][j].x * rs * gg[j].x, v[k][j].y * rs * gg[j].y); w.y = pk2(v[k][j].z * rs * gg[j].z, v[k][j].w * rs * gg[j].w); o8[64 * j] = w; } }
	v_pk_mul_f32 v[72:73], v[12:13], v[72:73]
	v_add_f32_e32 v96, v96, v97
	ds_bpermute_b32 v97, v92, v96
	v_pk_mul_f32 v[74:75], v[14:15], v[74:75]
	v_cvt_pk_bf16_f32 v72, v72, v73
	v_cvt_pk_bf16_f32 v73, v74, v75
	global_store_dwordx2 v[90:91], v[72:73], off
	s_waitcnt lgkmcnt(0)
	v_add_f32_e32 v72, v96, v97
	ds_bpermute_b32 v73, v95, v72
	v_pk_mul_f32 v[60:61], v[60:61], v[102:103] op_sel_hi:[1,0]
	v_pk_mul_f32 v[62:63], v[62:63], v[102:103] op_sel_hi:[1,0]
	s_waitcnt vmcnt(11)
	v_pk_mul_f32 v[60:61], v[8:9], v[60:61]
	v_pk_mul_f32 v[62:63], v[10:11], v[62:63]
	s_waitcnt lgkmcnt(0)
	v_add_f32_e32 v72, v72, v73
	ds_bpermute_b32 v73, v94, v72
	v_cvt_pk_bf16_f32 v60, v60, v61
	v_cvt_pk_bf16_f32 v61, v62, v63
	global_store_dwordx2 v[90:91], v[60:61], off offset:512
	v_pk_mul_f32 v[52:53], v[52:53], v[102:103] op_sel_hi:[1,0]
	s_waitcnt lgkmcnt(0)
	v_add_f32_e32 v60, v72, v73
	ds_bpermute_b32 v61, v93, v60
	v_pk_mul_f32 v[54:55], v[54:55], v[102:103] op_sel_hi:[1,0]
	s_waitcnt vmcnt(11)
	v_pk_mul_f32 v[52:53], v[4:5], v[52:53]
	v_pk_mul_f32 v[54:55], v[6:7], v[54:55]
	v_cvt_pk_bf16_f32 v52, v52, v53
	s_waitcnt lgkmcnt(0)
	v_add_f32_e32 v60, v60, v61
	ds_bpermute_b32 v61, v83, v60
	v_cvt_pk_bf16_f32 v53, v54, v55
	global_store_dwordx2 v[90:91], v[52:53], off offset:1024
	v_pk_mul_f32 v[40:41], v[40:41], v[102:103] op_sel_hi:[1,0]
	v_pk_mul_f32 v[42:43], v[42:43], v[102:103] op_sel_hi:[1,0]
	s_waitcnt lgkmcnt(0)
	v_add_f32_e32 v52, v60, v61
	ds_bpermute_b32 v53, v81, v52
	s_waitcnt vmcnt(11)
	v_pk_mul_f32 v[40:41], v[0:1], v[40:41]
	v_pk_mul_f32 v[42:43], v[2:3], v[42:43]
	v_cvt_pk_bf16_f32 v40, v40, v41
	v_cvt_pk_bf16_f32 v41, v42, v43
	s_waitcnt lgkmcnt(0)
	v_add_f32_e32 v42, v52, v53
	v_fmamk_f32 v42, v42, 0x3a800000, v230
	v_rsq_f32_e32 v42, v42
	s_waitcnt vmcnt(10)
	v_pk_mul_f32 v[52:53], v[70:71], v[70:71]
	v_pk_mul_f32 v[54:55], v[68:69], v[68:69]
	global_store_dwordx2 v[90:91], v[40:41], off offset:1536
	v_pk_mov_b32 v[60:61], v[54:55], v[52:53] op_sel:[1,0]
	v_mov_b32_e32 v55, v53
	v_pk_add_f32 v[52:53], v[60:61], v[54:55]
	s_waitcnt vmcnt(10)
	v_pk_mul_f32 v[54:55], v[58:59], v[58:59]
	v_pk_mul_f32 v[60:61], v[56:57], v[56:57]
	v_pk_mul_f32 v[24:25], v[24:25], v[42:43] op_sel_hi:[1,0]
	v_pk_mov_b32 v[62:63], v[60:61], v[54:55] op_sel:[1,0]
	v_mov_b32_e32 v61, v55
	v_pk_mul_f32 v[24:25], v[12:13], v[24:25]
	v_pk_add_f32 v[54:55], v[62:63], v[60:61]
	v_cvt_pk_bf16_f32 v24, v24, v25
	s_waitcnt vmcnt(8)
	v_mul_f32_e32 v25, v48, v48
	v_mul_f32_e32 v43, v49, v49
	v_pk_add_f32 v[52:53], v[52:53], v[52:53] op_sel:[0,1] op_sel_hi:[1,0]
	v_pk_add_f32 v[54:55], v[54:55], v[54:55] op_sel:[0,1] op_sel_hi:[1,0]
	v_mov_b32_e32 v53, v25
	v_mov_b32_e32 v55, v43
	v_pk_add_f32 v[52:53], v[52:53], v[54:55]
	v_mul_f32_e32 v54, v65, v65
	v_mul_f32_e32 v60, v50, v50
	v_pk_fma_f32 v[54:55], v[64:65], v[64:65], v[54:55] op_sel_hi:[1,1,0]
	v_mul_f32_e32 v62, v51, v51
	v_mov_b32_e32 v55, v60
	v_mul_f32_e32 v60, v67, v67
	v_pk_fma_f32 v[60:61], v[66:67], v[66:67], v[60:61] op_sel_hi:[1,1,0]
	v_lshl_add_u64 v[40:41], v[88:89], 0, s[20:21]
	v_mov_b32_e32 v61, v62
	v_pk_add_f32 v[54:55], v[54:55], v[60:61]
	s_lshl_b64 s[20:21], s[48:49], 11
	v_pk_add_f32 v[52:53], v[52:53], v[54:55]
	s_nop 0
	v_add_f32_e32 v43, v52, v53
	ds_bpermute_b32 v52, v92, v43
	v_pk_mul_f32 v[26:27], v[26:27], v[42:43] op_sel_hi:[1,0]
	v_pk_mul_f32 v[20:21], v[20:21], v[42:43] op_sel_hi:[1,0]
	v_pk_mul_f32 v[26:27], v[14:15], v[26:27]
	v_pk_mul_f32 v[22:23], v[22:23], v[42:43] op_sel_hi:[1,0]
	v_cvt_pk_bf16_f32 v25, v26, v27
	global_store_dwordx2 v[40:41], v[24:25], off
	s_waitcnt lgkmcnt(0)
	v_add_f32_e32 v24, v43, v52
	ds_bpermute_b32 v25, v95, v24
	v_pk_mul_f32 v[20:21], v[8:9], v[20:21]
	v_pk_mul_f32 v[22:23], v[10:11], v[22:23]
	v_cvt_pk_bf16_f32 v20, v20, v21
	v_cvt_pk_bf16_f32 v21, v22, v23
	s_waitcnt lgkmcnt(0)
	v_add_f32_e32 v24, v24, v25
	ds_bpermute_b32 v25, v94, v24
	global_store_dwordx2 v[40:41], v[20:21], off offset:512
	v_pk_mul_f32 v[20:21], v[76:77], v[42:43] op_sel_hi:[1,0]
	v_pk_mul_f32 v[22:23], v[78:79], v[42:43] op_sel_hi:[1,0]
	v_pk_mul_f32 v[20:21], v[4:5], v[20:21]
	s_waitcnt lgkmcnt(0)
	v_add_f32_e32 v24, v24, v25
	ds_bpermute_b32 v25, v93, v24
	v_pk_mul_f32 v[22:23], v[6:7], v[22:23]
	v_cvt_pk_bf16_f32 v20, v20, v21
	v_cvt_pk_bf16_f32 v21, v22, v23
	global_store_dwordx2 v[40:41], v[20:21], off offset:1024
	s_waitcnt lgkmcnt(0)
	v_add_f32_e32 v24, v24, v25
	ds_bpermute_b32 v25, v83, v24
	v_pk_mul_f32 v[16:17], v[16:17], v[42:43] op_sel_hi:[1,0]
	v_pk_mul_f32 v[18:19], v[18:19], v[42:43] op_sel_hi:[1,0]
	v_pk_mul_f32 v[16:17], v[0:1], v[16:17]
	v_pk_mul_f32 v[18:19], v[2:3], v[18:19]
	s_waitcnt lgkmcnt(0)
	v_add_f32_e32 v20, v24, v25
	ds_bpermute_b32 v21, v81, v20
	v_cvt_pk_bf16_f32 v16, v16, v17
	v_cvt_pk_bf16_f32 v17, v18, v19
	s_waitcnt vmcnt(10)
; __device__ __forceinline__ unsigned pk2(float lo, float hi) { f32x2_t v = {lo, hi}; bf16x2_t b = __builtin_convertvector(v, bf16x2_t); return __builtin_bit_cast(unsigned, b); }
; template <int NR>
; __device__ __forceinline__ void rms_rows_bf16(const float* x, const float* g, bf16* o, int m0, int mstride, int lane) {
;     ...
;     for (int k = 0; k < NR; ++k) { float s = 0.f;
; #pragma unroll
;         for (int j = 0; j < 4; ++j) s += (v[k][j].x * v[k][j].x + v[k][j].y * v[k][j].y) + (v[k][j].z * v[k][j].z + v[k][j].w * v[k][j].w);
;         const float rs = __builtin_amdgcn_rsqf(wave_sum(s) * (1.f / DM) + 1e-6f);
;         v2u* o8 = (v2u*)(o + (size_t)(m0 + k * mstride) * DM) + lane;
; #pragma unroll
;         for (int j = 0; j < 4; ++j) { v2u w; w.x = pk2(v[k][j].x * rs * gg[j].x, v[k][j].y * rs * gg[j].y); w.y = pk2(v[k][j].z * rs * gg[j].z, v[k][j].w * rs * gg[j].w); o8[64 * j] = w; } }
	v_pk_mul_f32 v[22:23], v[46:47], v[46:47]
	v_pk_mul_f32 v[24:25], v[44:45], v[44:45]
	s_waitcnt lgkmcnt(0)
	v_add_f32_e32 v18, v20, v21
	v_fmamk_f32 v18, v18, 0x3a800000, v230
	v_rsq_f32_e32 v18, v18
	v_pk_mov_b32 v[26:27], v[24:25], v[22:23] op_sel:[1,0]
	v_mov_b32_e32 v25, v23
	v_pk_add_f32 v[22:23], v[26:27], v[24:25]
	s_waitcnt vmcnt(9)
	v_pk_mul_f32 v[24:25], v[38:39], v[38:39]
	v_pk_mul_f32 v[26:27], v[36:37], v[36:37]
	global_store_dwordx2 v[40:41], v[16:17], off offset:1536
	v_pk_mul_f32 v[20:21], v[68:69], v[18:19] op_sel_hi:[1,0]
	v_pk_mov_b32 v[40:41], v[26:27], v[24:25] op_sel:[1,0]
	v_mov_b32_e32 v27, v25
	v_pk_mul_f32 v[20:21], v[12:13], v[20:21]
	v_pk_add_f32 v[24:25], v[40:41], v[26:27]
	v_cvt_pk_bf16_f32 v20, v20, v21
	s_waitcnt vmcnt(8)
	v_mul_f32_e32 v19, v28, v28
	v_mul_f32_e32 v21, v29, v29
	v_pk_add_f32 v[22:23], v[22:23], v[22:23] op_sel:[0,1] op_sel_hi:[1,0]
	v_pk_add_f32 v[24:25], v[24:25], v[24:25] op_sel:[0,1] op_sel_hi:[1,0]
	v_mov_b32_e32 v23, v19
	v_mov_b32_e32 v25, v21
	v_pk_add_f32 v[22:23], v[22:23], v[24:25]
	v_mul_f32_e32 v24, v33, v33
	v_mul_f32_e32 v26, v30, v30
	v_pk_fma_f32 v[24:25], v[32:33], v[32:33], v[24:25] op_sel_hi:[1,1,0]
	v_mul_f32_e32 v40, v31, v31
	v_mov_b32_e32 v25, v26
	v_mul_f32_e32 v26, v35, v35
	v_pk_fma_f32 v[26:27], v[34:35], v[34:35], v[26:27] op_sel_hi:[1,1,0]
	v_lshl_add_u64 v[16:17], v[88:89], 0, s[20:21]
	v_mov_b32_e32 v27, v40
	v_pk_add_f32 v[24:25], v[24:25], v[26:27]
	s_lshl_b64 s[20:21], s[42:43], 11
	v_pk_add_f32 v[22:23], v[22:23], v[24:25]
	s_cmpk_gt_i32 s19, 0x7fff
	v_add_f32_e32 v19, v22, v23
	ds_bpermute_b32 v24, v92, v19
	v_pk_mul_f32 v[22:23], v[70:71], v[18:19] op_sel_hi:[1,0]
	s_waitcnt lgkmcnt(0)
	v_add_f32_e32 v19, v19, v24
	ds_bpermute_b32 v24, v95, v19
	v_pk_mul_f32 v[22:23], v[14:15], v[22:23]
	s_nop 0
	v_cvt_pk_bf16_f32 v21, v22, v23
	global_store_dwordx2 v[16:17], v[20:21], off
	v_pk_mul_f32 v[20:21], v[56:57], v[18:19] op_sel_hi:[1,0]
	v_pk_mul_f32 v[22:23], v[58:59], v[18:19] op_sel_hi:[1,0]
	s_waitcnt lgkmcnt(0)
	v_add_f32_e32 v19, v19, v24
	ds_bpermute_b32 v24, v94, v19
	v_pk_mul_f32 v[20:21], v[8:9], v[20:21]
	v_pk_mul_f32 v[22:23], v[10:11], v[22:23]
	v_cvt_pk_bf16_f32 v20, v20, v21
	v_cvt_pk_bf16_f32 v21, v22, v23
	global_store_dwordx2 v[16:17], v[20:21], off offset:512
	v_pk_mul_f32 v[20:21], v[64:65], v[18:19] op_sel_hi:[1,0]
	s_waitcnt lgkmcnt(0)
	v_add_f32_e32 v19, v19, v24
	ds_bpermute_b32 v24, v93, v19
	v_pk_mul_f32 v[22:23], v[66:67], v[18:19] op_sel_hi:[1,0]
	v_pk_mul_f32 v[20:21], v[4:5], v[20:21]
	v_pk_mul_f32 v[22:23], v[6:7], v[22:23]
	v_cvt_pk_bf16_f32 v20, v20, v21
	s_waitcnt lgkmcnt(0)
	v_add_f32_e32 v19, v19, v24
	ds_bpermute_b32 v24, v83, v19
	v_cvt_pk_bf16_f32 v21, v22, v23
	global_store_dwordx2 v[16:17], v[20:21], off offset:1024
	v_pk_mul_f32 v[20:21], v[48:49], v[18:19] op_sel_hi:[1,0]
	s_waitcnt lgkmcnt(0)
	v_add_f32_e32 v22, v19, v24
	ds_bpermute_b32 v23, v81, v22
	v_pk_mul_f32 v[18:19], v[50:51], v[18:19] op_sel_hi:[1,0]
	v_pk_mul_f32 v[20:21], v[0:1], v[20:21]
	v_pk_mul_f32 v[18:19], v[2:3], v[18:19]
	v_cvt_pk_bf16_f32 v20, v20, v21
	v_cvt_pk_bf16_f32 v21, v18, v19
	s_waitcnt lgkmcnt(0)
	v_add_f32_e32 v18, v22, v23
	v_fmamk_f32 v18, v18, 0x3a800000, v230
	v_rsq_f32_e32 v18, v18
	global_store_dwordx2 v[16:17], v[20:21], off offset:1536
	v_lshl_add_u64 v[16:17], v[88:89], 0, s[20:21]
	v_pk_mul_f32 v[20:21], v[44:45], v[18:19] op_sel_hi:[1,0]
	s_nop 0
	v_pk_mul_f32 v[12:13], v[12:13], v[20:21]
	v_pk_mul_f32 v[20:21], v[46:47], v[18:19] op_sel_hi:[1,0]
	v_cvt_pk_bf16_f32 v12, v12, v13
	v_pk_mul_f32 v[14:15], v[14:15], v[20:21]
	s_nop 0
	v_cvt_pk_bf16_f32 v13, v14, v15
	global_store_dwordx2 v[16:17], v[12:13], off
	v_pk_mul_f32 v[12:13], v[36:37], v[18:19] op_sel_hi:[1,0]
	s_nop 0
	v_pk_mul_f32 v[8:9], v[8:9], v[12:13]
	v_pk_mul_f32 v[12:13], v[38:39], v[18:19] op_sel_hi:[1,0]
	v_cvt_pk_bf16_f32 v8, v8, v9
	v_pk_mul_f32 v[10:11], v[10:11], v[12:13]
	s_nop 0
	v_cvt_pk_bf16_f32 v9, v10, v11
	global_store_dwordx2 v[16:17], v[8:9], off offset:512
	v_pk_mul_f32 v[8:9], v[32:33], v[18:19] op_sel_hi:[1,0]
	s_nop 0
	v_pk_mul_f32 v[4:5], v[4:5], v[8:9]
	v_pk_mul_f32 v[8:9], v[34:35], v[18:19] op_sel_hi:[1,0]
	v_cvt_pk_bf16_f32 v4, v4, v5
	v_pk_mul_f32 v[6:7], v[6:7], v[8:9]
	s_nop 0
	v_cvt_pk_bf16_f32 v5, v6, v7
	global_store_dwordx2 v[16:17], v[4:5], off offset:1024
	v_pk_mul_f32 v[4:5], v[28:29], v[18:19] op_sel_hi:[1,0]
	s_nop 0
	v_pk_mul_f32 v[0:1], v[0:1], v[4:5]
	v_pk_mul_f32 v[4:5], v[30:31], v[18:19] op_sel_hi:[1,0]
	v_cvt_pk_bf16_f32 v0, v0, v1
	v_pk_mul_f32 v[2:3], v[2:3], v[4:5]
	s_nop 0
	v_cvt_pk_bf16_f32 v1, v2, v3
	global_store_dwordx2 v[16:17], v[0:1], off offset:1536
	s_cbranch_scc0 .LBB0_58
	s_branch .LBB0_60

; __device__ __forceinline__ unsigned pk2(float lo, float hi) { f32x2_t v = {lo, hi}; bf16x2_t b = __builtin_convertvector(v, bf16x2_t); return __builtin_bit_cast(unsigned, b); }
; template <int NR>
; __device__ __forceinline__ void rms_rows_bf16(const float* x, const float* g, bf16* o, int m0, int mstride, int lane) {
;     ...
;     for (int k = 0; k < NR; ++k) { const f32x4* xr = (const f32x4*)(x + (size_t)(m0 + k * mstride) * DM) + lane;
; #pragma unroll
;         for (int j = 0; j < 4; ++j) v[k][j] = xr[64 * j]; }
;     f32x4 gg[4];
; #pragma unroll
;     for (int j = 0; j < 4; ++j) gg[j] = gr[64 * j];
; #pragma unroll
;     for (int k = 0; k < NR; ++k) { float s = 0.f;
; #pragma unroll
;         for (int j = 0; j < 4; ++j) s += (v[k][j].x * v[k][j].x + v[k][j].y * v[k][j].y) + (v[k][j].z * v[k][j].z + v[k][j].w * v[k][j].w);
;         const float rs = __builtin_amdgcn_rsqf(wave_sum(s) * (1.f / DM) + 1e-6f);
;         v2u* o8 = (v2u*)(o + (size_t)(m0 + k * mstride) * DM) + lane;
; #pragma unroll
;         for (int j = 0; j < 4; ++j) { v2u w; w.x = pk2(v[k][j].x * rs * gg[j].x, v[k][j].y * rs * gg[j].y); w.y = pk2(v[k][j].z * rs * gg[j].z, v[k][j].w * rs * gg[j].w); o8[64 * j] = w; } }
.LBB0_62:
	s_mov_b64 s[42:43], 0
	global_load_dwordx4 v[6:9], v[2:3], off offset:-2048 nt
	global_load_dwordx4 v[10:13], v[2:3], off offset:-1024 nt
	global_load_dwordx4 v[14:17], v[2:3], off nt
	global_load_dwordx4 v[18:21], v[2:3], off offset:1024 nt
	v_and_b32_e32 v22, 64, v228
	v_xor_b32_e32 v23, 1, v228
	v_add_u32_e32 v22, 64, v22
	v_xor_b32_e32 v24, 2, v228
	v_cmp_lt_i32_e32 vcc, v23, v22
	v_xor_b32_e32 v25, 4, v228
	v_xor_b32_e32 v26, 8, v228
	v_cndmask_b32_e32 v38, v228, v23, vcc
	v_cmp_lt_i32_e32 vcc, v24, v22
	v_xor_b32_e32 v27, 16, v228
	v_xor_b32_e32 v28, 32, v228
	v_cndmask_b32_e32 v39, v228, v24, vcc
	v_cmp_lt_i32_e32 vcc, v25, v22
	v_lshl_add_u64 v[34:35], s[42:43], 2, v[0:1]
	v_lshlrev_b32_e32 v49, 2, v38
	v_cndmask_b32_e32 v40, v228, v25, vcc
	v_cmp_lt_i32_e32 vcc, v26, v22
	v_lshlrev_b32_e32 v52, 2, v39
	v_lshlrev_b32_e32 v53, 2, v40
	v_cndmask_b32_e32 v41, v228, v26, vcc
	v_cmp_lt_i32_e32 vcc, v27, v22
	v_lshlrev_b32_e32 v54, 2, v41
	s_add_i32 s38, s38, s76
	v_cndmask_b32_e32 v42, v228, v27, vcc
	v_cmp_lt_i32_e32 vcc, v28, v22
	v_lshlrev_b32_e32 v55, 2, v42
	v_lshl_add_u64 v[2:3], v[2:3], 0, s[8:9]
	v_cndmask_b32_e32 v43, v228, v28, vcc
	global_load_dwordx4 v[22:25], v[34:35], off nt
	global_load_dwordx4 v[26:29], v[34:35], off offset:1024 nt
	global_load_dwordx4 v[30:33], v[34:35], off offset:2048 nt
	s_nop 0
	global_load_dwordx4 v[34:37], v[34:35], off offset:3072 nt
	v_lshlrev_b32_e32 v56, 2, v43
	s_cmp_lt_i32 s38, 0x8000
	s_waitcnt vmcnt(7)
	v_pk_mul_f32 v[38:39], v[8:9], v[8:9]
	v_pk_mul_f32 v[40:41], v[6:7], v[6:7]
	s_waitcnt vmcnt(6)
	v_pk_mul_f32 v[42:43], v[12:13], v[12:13]
	v_pk_mul_f32 v[44:45], v[10:11], v[10:11]
	v_pk_mov_b32 v[50:51], v[40:41], v[38:39] op_sel:[1,0]
	v_mov_b32_e32 v41, v39
	v_pk_mov_b32 v[38:39], v[44:45], v[42:43] op_sel:[1,0]
	v_mov_b32_e32 v45, v43
	s_waitcnt vmcnt(5)
	v_mul_f32_e32 v46, v15, v15
	v_mul_f32_e32 v48, v17, v17
	v_pk_add_f32 v[40:41], v[50:51], v[40:41]
	v_pk_add_f32 v[38:39], v[38:39], v[44:45]
	s_waitcnt vmcnt(4)
	v_mul_f32_e32 v57, v18, v18
	v_mul_f32_e32 v58, v19, v19
	v_mul_f32_e32 v59, v20, v20
	v_mul_f32_e32 v60, v21, v21
	v_pk_fma_f32 v[42:43], v[14:15], v[14:15], v[46:47] op_sel_hi:[1,1,0]
	v_pk_fma_f32 v[46:47], v[16:17], v[16:17], v[48:49] op_sel_hi:[1,1,0]
	v_pk_add_f32 v[40:41], v[40:41], v[40:41] op_sel:[0,1] op_sel_hi:[1,0]
	v_pk_add_f32 v[38:39], v[38:39], v[38:39] op_sel:[0,1] op_sel_hi:[1,0]
	v_mov_b32_e32 v43, v59
	v_mov_b32_e32 v47, v60
	v_mov_b32_e32 v41, v57
	v_mov_b32_e32 v39, v58
	v_pk_add_f32 v[42:43], v[42:43], v[46:47]
	v_pk_add_f32 v[38:39], v[40:41], v[38:39]
	s_nop 0
	v_pk_add_f32 v[38:39], v[38:39], v[42:43]
	s_nop 0
	v_add_f32_e32 v38, v38, v39
	ds_bpermute_b32 v39, v49, v38
	s_waitcnt lgkmcnt(0)
	v_add_f32_e32 v38, v38, v39
	ds_bpermute_b32 v39, v52, v38
	s_waitcnt lgkmcnt(0)
	v_add_f32_e32 v38, v38, v39
	ds_bpermute_b32 v39, v53, v38
	s_waitcnt lgkmcnt(0)
	v_add_f32_e32 v38, v38, v39
	ds_bpermute_b32 v39, v54, v38
	s_waitcnt lgkmcnt(0)
	v_add_f32_e32 v38, v38, v39
	ds_bpermute_b32 v39, v55, v38
	s_waitcnt lgkmcnt(0)
	v_add_f32_e32 v38, v38, v39
	ds_bpermute_b32 v39, v56, v38
	s_waitcnt lgkmcnt(0)
	v_add_f32_e32 v38, v38, v39
	v_fmamk_f32 v38, v38, 0x3a800000, v230
	v_rsq_f32_e32 v38, v38
	s_nop 0
	v_pk_mul_f32 v[6:7], v[6:7], v[38:39] op_sel_hi:[1,0]
	v_pk_mul_f32 v[8:9], v[8:9], v[38:39] op_sel_hi:[1,0]
	v_pk_mul_f32 v[10:11], v[10:11], v[38:39] op_sel_hi:[1,0]
	v_pk_mul_f32 v[12:13], v[12:13], v[38:39] op_sel_hi:[1,0]
	v_pk_mul_f32 v[14:15], v[14:15], v[38:39] op_sel_hi:[1,0]
	v_pk_mul_f32 v[16:17], v[16:17], v[38:39] op_sel_hi:[1,0]
	v_pk_mul_f32 v[18:19], v[18:19], v[38:39] op_sel_hi:[1,0]
	v_pk_mul_f32 v[20:21], v[20:21], v[38:39] op_sel_hi:[1,0]
	s_waitcnt vmcnt(3)
	v_pk_mul_f32 v[6:7], v[22:23], v[6:7]
	v_pk_mul_f32 v[8:9], v[24:25], v[8:9]
	s_waitcnt vmcnt(2)
	v_pk_mul_f32 v[10:11], v[26:27], v[10:11]
	v_pk_mul_f32 v[12:13], v[28:29], v[12:13]
	s_waitcnt vmcnt(1)
	v_pk_mul_f32 v[14:15], v[30:31], v[14:15]
	v_pk_mul_f32 v[16:17], v[32:33], v[16:17]
	s_waitcnt vmcnt(0)
	v_pk_mul_f32 v[18:19], v[34:35], v[18:19]
	v_pk_mul_f32 v[20:21], v[36:37], v[20:21]
	v_cvt_pk_bf16_f32 v6, v6, v7
	v_cvt_pk_bf16_f32 v7, v8, v9
	v_cvt_pk_bf16_f32 v8, v10, v11
	v_cvt_pk_bf16_f32 v9, v12, v13
	v_cvt_pk_bf16_f32 v10, v14, v15
	v_cvt_pk_bf16_f32 v11, v16, v17
	v_cvt_pk_bf16_f32 v12, v18, v19
	v_cvt_pk_bf16_f32 v13, v20, v21
	global_store_dwordx2 v[4:5], v[6:7], off offset:-1024
	global_store_dwordx2 v[4:5], v[8:9], off offset:-512
	global_store_dwordx2 v[4:5], v[10:11], off
	global_store_dwordx2 v[4:5], v[12:13], off offset:512
	v_lshl_add_u64 v[4:5], v[4:5], 0, s[6:7]
	s_cbranch_scc1 .LBB0_62
	v_readlane_b32 s58, v247, 1
	v_readlane_b32 s59, v247, 2
	s_mov_b64 s[44:45], s[28:29]
	s_mov_b32 s46, s30

; template <int NR>
; __device__ __forceinline__ void rms_rows_bf16(const float* x, const float* g, bf16* o, int m0, int mstride, int lane) {
;     ...
;     for (int k = 0; k < NR; ++k) { const f32x4* xr = (const f32x4*)(x + (size_t)(m0 + k * mstride) * DM) + lane;
; #pragma unroll
;         for (int j = 0; j < 4; ++j) v[k][j] = xr[64 * j]; }
;     f32x4 gg[4];
; #pragma unroll
;     for (int j = 0; j < 4; ++j) gg[j] = gr[64 * j];
; #pragma unroll
;     for (int k = 0; k < NR; ++k) { float s = 0.f;
; #pragma unroll
;         for (int j = 0; j < 4; ++j) s += (v[k][j].x * v[k][j].x + v[k][j].y * v[k][j].y) + (v[k][j].z * v[k][j].z + v[k][j].w * v[k][j].w);
;         const float rs = __builtin_amdgcn_rsqf(wave_sum(s) * (1.f / DM) + 1e-6f);
.LBB0_826:
	s_ashr_i32 s45, s44, 31
	s_lshl_b64 s[20:21], s[44:45], 12
	s_mov_b64 s[50:51], 0
	v_lshl_add_u64 v[0:1], v[82:83], 0, s[20:21]
	global_load_dwordx4 v[76:79], v[0:1], off nt
	global_load_dwordx4 v[72:75], v[0:1], off offset:1024 nt
	global_load_dwordx4 v[68:71], v[0:1], off offset:2048 nt
	global_load_dwordx4 v[64:67], v[0:1], off offset:3072 nt
	s_add_i32 s48, s44, s76
	s_ashr_i32 s49, s48, 31
	s_add_i32 s46, s4, s44
	s_lshl_b64 s[20:21], s[48:49], 12
	s_ashr_i32 s47, s46, 31
	s_add_i32 s42, s34, s44
	v_lshl_add_u64 v[0:1], v[82:83], 0, s[20:21]
	s_lshl_b64 s[20:21], s[46:47], 12
	s_ashr_i32 s43, s42, 31
	global_load_dwordx4 v[60:63], v[0:1], off nt
	global_load_dwordx4 v[56:59], v[0:1], off offset:1024 nt
	global_load_dwordx4 v[52:55], v[0:1], off offset:2048 nt
	global_load_dwordx4 v[48:51], v[0:1], off offset:3072 nt
	v_lshl_add_u64 v[0:1], v[82:83], 0, s[20:21]
	s_lshl_b64 s[20:21], s[42:43], 12
	global_load_dwordx4 v[44:47], v[0:1], off nt
	global_load_dwordx4 v[40:43], v[0:1], off offset:1024 nt
	global_load_dwordx4 v[36:39], v[0:1], off offset:2048 nt
	global_load_dwordx4 v[32:35], v[0:1], off offset:3072 nt
	v_lshl_add_u64 v[0:1], v[82:83], 0, s[20:21]
	v_lshl_add_u64 v[4:5], s[50:51], 2, v[84:85]
	global_load_dwordx4 v[24:27], v[0:1], off nt
	global_load_dwordx4 v[16:19], v[0:1], off offset:1024 nt
	global_load_dwordx4 v[8:11], v[0:1], off offset:2048 nt
	s_nop 0
	global_load_dwordx4 v[0:3], v[0:1], off offset:3072 nt
	s_nop 0
	global_load_dwordx4 v[28:31], v[4:5], off nt
	global_load_dwordx4 v[20:23], v[4:5], off offset:1024 nt
	global_load_dwordx4 v[12:15], v[4:5], off offset:2048 nt
	s_nop 0
	global_load_dwordx4 v[4:7], v[4:5], off offset:3072 nt
	v_and_b32_e32 v81, 64, v228
	v_add_u32_e32 v88, 64, v81
	v_xor_b32_e32 v81, 1, v228
	v_cmp_lt_i32_e32 vcc, v81, v88
	v_xor_b32_e32 v91, 8, v228
	v_xor_b32_e32 v92, 16, v228
	v_cndmask_b32_e32 v81, v228, v81, vcc
	v_lshlrev_b32_e32 v90, 2, v81
	v_xor_b32_e32 v81, 2, v228
	v_cmp_lt_i32_e32 vcc, v81, v88
	s_lshl_b64 s[20:21], s[44:45], 11
	s_add_i32 s19, s48, s76
	v_cndmask_b32_e32 v81, v228, v81, vcc
	v_lshlrev_b32_e32 v89, 2, v81
	v_xor_b32_e32 v81, 4, v228
	v_cmp_lt_i32_e32 vcc, v81, v88
	s_add_i32 s19, s19, s76
	s_add_i32 s44, s19, s76
	v_cndmask_b32_e32 v81, v228, v81, vcc
	v_cmp_lt_i32_e32 vcc, v91, v88
	v_lshlrev_b32_e32 v81, 2, v81
	s_add_i32 s19, s34, s44
	v_cndmask_b32_e32 v91, v228, v91, vcc
	v_cmp_lt_i32_e32 vcc, v92, v88
	v_lshlrev_b32_e32 v91, 2, v91
	s_waitcnt vmcnt(19)
	v_pk_mul_f32 v[94:95], v[78:79], v[78:79]
	v_pk_mul_f32 v[96:97], v[76:77], v[76:77]
	v_cndmask_b32_e32 v92, v228, v92, vcc
	v_pk_mov_b32 v[98:99], v[96:97], v[94:95] op_sel:[1,0]
	v_mov_b32_e32 v97, v95
	v_lshlrev_b32_e32 v93, 2, v92
	v_xor_b32_e32 v92, 32, v228
	v_pk_add_f32 v[94:95], v[98:99], v[96:97]
	s_waitcnt vmcnt(18)
	v_pk_mul_f32 v[96:97], v[74:75], v[74:75]
	v_pk_mul_f32 v[98:99], v[72:73], v[72:73]
	v_cmp_lt_i32_e32 vcc, v92, v88
	v_pk_mov_b32 v[100:101], v[98:99], v[96:97] op_sel:[1,0]
	v_mov_b32_e32 v99, v97
	v_cndmask_b32_e32 v88, v228, v92, vcc
	v_pk_add_f32 v[96:97], v[100:101], v[98:99]
	v_lshlrev_b32_e32 v92, 2, v88
	s_waitcnt vmcnt(16)
	v_mul_f32_e32 v88, v64, v64
	v_mul_f32_e32 v98, v65, v65
	v_pk_add_f32 v[94:95], v[94:95], v[94:95] op_sel:[0,1] op_sel_hi:[1,0]
	v_pk_add_f32 v[96:97], v[96:97], v[96:97] op_sel:[0,1] op_sel_hi:[1,0]
	v_mov_b32_e32 v95, v88
	v_mov_b32_e32 v97, v98
	v_mul_f32_e32 v88, v69, v69
	v_mul_f32_e32 v99, v66, v66
	v_pk_add_f32 v[94:95], v[94:95], v[96:97]
	v_pk_fma_f32 v[96:97], v[68:69], v[68:69], v[88:89] op_sel_hi:[1,1,0]
	v_mul_f32_e32 v88, v71, v71
	v_mul_f32_e32 v100, v67, v67
	v_mov_b32_e32 v97, v99
	v_pk_fma_f32 v[98:99], v[70:71], v[70:71], v[88:89] op_sel_hi:[1,1,0]
	s_nop 0
	v_mov_b32_e32 v99, v100
	v_pk_add_f32 v[96:97], v[96:97], v[98:99]
	s_nop 0
	v_pk_add_f32 v[94:95], v[94:95], v[96:97]
	s_nop 0
	v_add_f32_e32 v88, v94, v95
	ds_bpermute_b32 v94, v90, v88
	s_waitcnt lgkmcnt(0)
	v_add_f32_e32 v88, v88, v94
	ds_bpermute_b32 v94, v89, v88
	s_waitcnt lgkmcnt(0)
	v_add_f32_e32 v88, v88, v94
	ds_bpermute_b32 v94, v81, v88
	s_waitcnt lgkmcnt(0)
	v_add_f32_e32 v88, v88, v94
	ds_bpermute_b32 v94, v91, v88
	s_waitcnt lgkmcnt(0)
	v_add_f32_e32 v88, v88, v94
	ds_bpermute_b32 v94, v93, v88
	s_waitcnt lgkmcnt(0)
	v_add_f32_e32 v88, v88, v94
	ds_bpermute_b32 v94, v92, v88
	s_waitcnt lgkmcnt(0)
	v_add_f32_e32 v88, v88, v94
	v_fmamk_f32 v88, v88, 0x3a800000, v230
	v_rsq_f32_e32 v88, v88
	v_lshl_add_u64 v[94:95], v[86:87], 0, s[20:21]
	s_lshl_b64 s[20:21], s[48:49], 11
	v_pk_mul_f32 v[64:65], v[64:65], v[88:89] op_sel_hi:[1,0]
	v_pk_mul_f32 v[66:67], v[66:67], v[88:89] op_sel_hi:[1,0]
	v_pk_mul_f32 v[68:69], v[68:69], v[88:89] op_sel_hi:[1,0]
	v_pk_mul_f32 v[70:71], v[70:71], v[88:89] op_sel_hi:[1,0]
	s_waitcnt vmcnt(0)
; __device__ __forceinline__ unsigned pk2(float lo, float hi) { f32x2_t v = {lo, hi}; bf16x2_t b = __builtin_convertvector(v, bf16x2_t); return __builtin_bit_cast(unsigned, b); }
; template <int NR>
; __device__ __forceinline__ void rms_rows_bf16(const float* x, const float* g, bf16* o, int m0, int mstride, int lane) {
;     ...
;     for (int k = 0; k < NR; ++k) { float s = 0.f;
; #pragma unroll
;         for (int j = 0; j < 4; ++j) s += (v[k][j].x * v[k][j].x + v[k][j].y * v[k][j].y) + (v[k][j].z * v[k][j].z + v[k][j].w * v[k][j].w);
;         const float rs = __builtin_amdgcn_rsqf(wave_sum(s) * (1.f / DM) + 1e-6f);
;         v2u* o8 = (v2u*)(o + (size_t)(m0 + k * mstride) * DM) + lane;
; #pragma unroll
;         for (int j = 0; j < 4; ++j) { v2u w; w.x = pk2(v[k][j].x * rs * gg[j].x, v[k][j].y * rs * gg[j].y); w.y = pk2(v[k][j].z * rs * gg[j].z, v[k][j].w * rs * gg[j].w); o8[64 * j] = w; } }
	v_pk_mul_f32 v[64:65], v[4:5], v[64:65]
	v_pk_mul_f32 v[66:67], v[6:7], v[66:67]
	v_pk_mul_f32 v[68:69], v[12:13], v[68:69]
	v_pk_mul_f32 v[70:71], v[14:15], v[70:71]
	v_cvt_pk_bf16_f32 v64, v64, v65
	v_cvt_pk_bf16_f32 v65, v66, v67
	v_cvt_pk_bf16_f32 v68, v68, v69
	v_cvt_pk_bf16_f32 v69, v70, v71
	global_store_dwordx2 v[94:95], v[64:65], off offset:1536
	v_pk_mul_f32 v[64:65], v[62:63], v[62:63]
	v_pk_mul_f32 v[66:67], v[60:61], v[60:61]
	global_store_dwordx2 v[94:95], v[68:69], off offset:1024
	v_pk_mov_b32 v[68:69], v[66:67], v[64:65] op_sel:[1,0]
	v_mov_b32_e32 v67, v65
	v_pk_add_f32 v[64:65], v[68:69], v[66:67]
	v_pk_mul_f32 v[66:67], v[58:59], v[58:59]
	v_pk_mul_f32 v[68:69], v[56:57], v[56:57]
	v_pk_add_f32 v[64:65], v[64:65], v[64:65] op_sel:[0,1] op_sel_hi:[1,0]
	v_pk_mov_b32 v[70:71], v[68:69], v[66:67] op_sel:[1,0]
	v_mov_b32_e32 v69, v67
	v_pk_add_f32 v[66:67], v[70:71], v[68:69]
	v_mul_f32_e32 v68, v48, v48
	v_mul_f32_e32 v69, v49, v49
	v_pk_add_f32 v[66:67], v[66:67], v[66:67] op_sel:[0,1] op_sel_hi:[1,0]
	v_mov_b32_e32 v65, v68
	v_mov_b32_e32 v67, v69
	v_pk_add_f32 v[64:65], v[64:65], v[66:67]
	v_mul_f32_e32 v66, v53, v53
	v_mul_f32_e32 v68, v55, v55
	v_mul_f32_e32 v70, v50, v50
	v_mul_f32_e32 v71, v51, v51
	v_pk_fma_f32 v[66:67], v[52:53], v[52:53], v[66:67] op_sel_hi:[1,1,0]
	v_pk_fma_f32 v[68:69], v[54:55], v[54:55], v[68:69] op_sel_hi:[1,1,0]
	v_mov_b32_e32 v67, v70
	v_mov_b32_e32 v69, v71
	v_pk_add_f32 v[66:67], v[66:67], v[68:69]
	v_pk_mul_f32 v[76:77], v[76:77], v[88:89] op_sel_hi:[1,0]
	v_pk_add_f32 v[64:65], v[64:65], v[66:67]
	v_lshl_add_u64 v[66:67], v[86:87], 0, s[20:21]
	v_add_f32_e32 v64, v64, v65
	ds_bpermute_b32 v65, v90, v64
	s_lshl_b64 s[20:21], s[46:47], 11
	v_pk_mul_f32 v[78:79], v[78:79], v[88:89] op_sel_hi:[1,0]
	v_pk_mul_f32 v[72:73], v[72:73], v[88:89] op_sel_hi:[1,0]
	v_pk_mul_f32 v[74:75], v[74:75], v[88:89] op_sel_hi:[1,0]
	s_waitcnt lgkmcnt(0)
	v_add_f32_e32 v64, v64, v65
	ds_bpermute_b32 v65, v89, v64
	v_pk_mul_f32 v[76:77], v[28:29], v[76:77]
	v_pk_mul_f32 v[78:79], v[30:31], v[78:79]
	v_pk_mul_f32 v[72:73], v[20:21], v[72:73]
	v_pk_mul_f32 v[74:75], v[22:23], v[74:75]
	s_waitcnt lgkmcnt(0)
	v_add_f32_e32 v64, v64, v65
	ds_bpermute_b32 v65, v81, v64
	v_cvt_pk_bf16_f32 v76, v76, v77
	v_cvt_pk_bf16_f32 v77, v78, v79
	v_cvt_pk_bf16_f32 v72, v72, v73
	v_cvt_pk_bf16_f32 v73, v74, v75
	s_waitcnt lgkmcnt(0)
	v_add_f32_e32 v64, v64, v65
	ds_bpermute_b32 v65, v91, v64
	global_store_dwordx2 v[94:95], v[76:77], off
	global_store_dwordx2 v[94:95], v[72:73], off offset:512
	s_waitcnt lgkmcnt(0)
	v_add_f32_e32 v64, v64, v65
	ds_bpermute_b32 v65, v93, v64
	s_waitcnt lgkmcnt(0)
	v_add_f32_e32 v64, v64, v65
	ds_bpermute_b32 v65, v92, v64
	s_waitcnt lgkmcnt(0)
	v_add_f32_e32 v64, v64, v65
	v_fmamk_f32 v64, v64, 0x3a800000, v230
	v_rsq_f32_e32 v64, v64
	s_nop 0
	v_pk_mul_f32 v[48:49], v[48:49], v[64:65] op_sel_hi:[1,0]
	v_pk_mul_f32 v[50:51], v[50:51], v[64:65] op_sel_hi:[1,0]
	v_pk_mul_f32 v[52:53], v[52:53], v[64:65] op_sel_hi:[1,0]
	v_pk_mul_f32 v[54:55], v[54:55], v[64:65] op_sel_hi:[1,0]
	v_pk_mul_f32 v[48:49], v[4:5], v[48:49]
	v_pk_mul_f32 v[50:51], v[6:7], v[50:51]
	v_pk_mul_f32 v[52:53], v[12:13], v[52:53]
	v_pk_mul_f32 v[54:55], v[14:15], v[54:55]
	v_cvt_pk_bf16_f32 v48, v48, v49
	v_cvt_pk_bf16_f32 v49, v50, v51
	v_cvt_pk_bf16_f32 v52, v52, v53
	v_cvt_pk_bf16_f32 v53, v54, v55
	global_store_dwordx2 v[66:67], v[48:49], off offset:1536
	v_pk_mul_f32 v[48:49], v[46:47], v[46:47]
	v_pk_mul_f32 v[50:51], v[44:45], v[44:45]
	global_store_dwordx2 v[66:67], v[52:53], off offset:1024
	v_pk_mov_b32 v[52:53], v[50:51], v[48:49] op_sel:[1,0]
	v_mov_b32_e32 v51, v49
	v_pk_add_f32 v[48:49], v[52:53], v[50:51]
	v_pk_mul_f32 v[50:51], v[42:43], v[42:43]
	v_pk_mul_f32 v[52:53], v[40:41], v[40:41]
	v_pk_add_f32 v[48:49], v[48:49], v[48:49] op_sel:[0,1] op_sel_hi:[1,0]
	v_pk_mov_b32 v[54:55], v[52:53], v[50:51] op_sel:[1,0]
	v_mov_b32_e32 v53, v51
	v_pk_add_f32 v[50:51], v[54:55], v[52:53]
	v_mul_f32_e32 v52, v32, v32
	v_mul_f32_e32 v53, v33, v33
	v_pk_add_f32 v[50:51], v[50:51], v[50:51] op_sel:[0,1] op_sel_hi:[1,0]
	v_mov_b32_e32 v49, v52
	v_mov_b32_e32 v51, v53
	v_pk_add_f32 v[48:49], v[48:49], v[50:51]
	v_mul_f32_e32 v50, v37, v37
	v_mul_f32_e32 v52, v39, v39
	v_mul_f32_e32 v54, v34, v34
	v_mul_f32_e32 v55, v35, v35
	v_pk_fma_f32 v[50:51], v[36:37], v[36:37], v[50:51] op_sel_hi:[1,1,0]
	v_pk_fma_f32 v[52:53], v[38:39], v[38:39], v[52:53] op_sel_hi:[1,1,0]
	v_mov_b32_e32 v51, v54
	v_mov_b32_e32 v53, v55
	v_pk_add_f32 v[50:51], v[50:51], v[52:53]
	v_pk_mul_f32 v[60:61], v[60:61], v[64:65] op_sel_hi:[1,0]
	v_pk_add_f32 v[48:49], v[48:49], v[50:51]
	v_lshl_add_u64 v[50:51], v[86:87], 0, s[20:21]
	v_add_f32_e32 v48, v48, v49
	ds_bpermute_b32 v49, v90, v48
	v_pk_mul_f32 v[62:63], v[62:63], v[64:65] op_sel_hi:[1,0]
	v_pk_mul_f32 v[56:57], v[56:57], v[64:65] op_sel_hi:[1,0]
	v_pk_mul_f32 v[58:59], v[58:59], v[64:65] op_sel_hi:[1,0]
	v_pk_mul_f32 v[60:61], v[28:29], v[60:61]
	s_waitcnt lgkmcnt(0)
	v_add_f32_e32 v48, v48, v49
	ds_bpermute_b32 v49, v89, v48
	v_pk_mul_f32 v[62:63], v[30:31], v[62:63]
	v_pk_mul_f32 v[56:57], v[20:21], v[56:57]
	v_pk_mul_f32 v[58:59], v[22:23], v[58:59]
	s_lshl_b64 s[20:21], s[42:43], 11
	s_waitcnt lgkmcnt(0)
; __device__ __forceinline__ unsigned pk2(float lo, float hi) { f32x2_t v = {lo, hi}; bf16x2_t b = __builtin_convertvector(v, bf16x2_t); return __builtin_bit_cast(unsigned, b); }
; template <int NR>
; __device__ __forceinline__ void rms_rows_bf16(const float* x, const float* g, bf16* o, int m0, int mstride, int lane) {
;     ...
;     for (int k = 0; k < NR; ++k) { float s = 0.f;
; #pragma unroll
;         for (int j = 0; j < 4; ++j) s += (v[k][j].x * v[k][j].x + v[k][j].y * v[k][j].y) + (v[k][j].z * v[k][j].z + v[k][j].w * v[k][j].w);
;         const float rs = __builtin_amdgcn_rsqf(wave_sum(s) * (1.f / DM) + 1e-6f);
;         v2u* o8 = (v2u*)(o + (size_t)(m0 + k * mstride) * DM) + lane;
; #pragma unroll
;         for (int j = 0; j < 4; ++j) { v2u w; w.x = pk2(v[k][j].x * rs * gg[j].x, v[k][j].y * rs * gg[j].y); w.y = pk2(v[k][j].z * rs * gg[j].z, v[k][j].w * rs * gg[j].w); o8[64 * j] = w; } }
	v_add_f32_e32 v48, v48, v49
	ds_bpermute_b32 v49, v81, v48
	v_cvt_pk_bf16_f32 v60, v60, v61
	v_cvt_pk_bf16_f32 v61, v62, v63
	v_cvt_pk_bf16_f32 v56, v56, v57
	v_cvt_pk_bf16_f32 v57, v58, v59
	s_waitcnt lgkmcnt(0)
	v_add_f32_e32 v48, v48, v49
	ds_bpermute_b32 v49, v91, v48
	s_cmpk_gt_i32 s19, 0x7fff
	global_store_dwordx2 v[66:67], v[60:61], off
	global_store_dwordx2 v[66:67], v[56:57], off offset:512
	s_waitcnt lgkmcnt(0)
	v_add_f32_e32 v48, v48, v49
	ds_bpermute_b32 v49, v93, v48
	s_waitcnt lgkmcnt(0)
	v_add_f32_e32 v48, v48, v49
	ds_bpermute_b32 v49, v92, v48
	s_waitcnt lgkmcnt(0)
	v_add_f32_e32 v48, v48, v49
	v_fmamk_f32 v48, v48, 0x3a800000, v230
	v_rsq_f32_e32 v48, v48
	s_nop 0
	v_pk_mul_f32 v[32:33], v[32:33], v[48:49] op_sel_hi:[1,0]
	v_pk_mul_f32 v[34:35], v[34:35], v[48:49] op_sel_hi:[1,0]
	v_pk_mul_f32 v[36:37], v[36:37], v[48:49] op_sel_hi:[1,0]
	v_pk_mul_f32 v[38:39], v[38:39], v[48:49] op_sel_hi:[1,0]
	v_pk_mul_f32 v[32:33], v[4:5], v[32:33]
	v_pk_mul_f32 v[34:35], v[6:7], v[34:35]
	v_pk_mul_f32 v[36:37], v[12:13], v[36:37]
	v_pk_mul_f32 v[38:39], v[14:15], v[38:39]
	v_cvt_pk_bf16_f32 v32, v32, v33
	v_cvt_pk_bf16_f32 v33, v34, v35
	v_cvt_pk_bf16_f32 v36, v36, v37
	v_cvt_pk_bf16_f32 v37, v38, v39
	global_store_dwordx2 v[50:51], v[32:33], off offset:1536
	v_pk_mul_f32 v[32:33], v[26:27], v[26:27]
	v_pk_mul_f32 v[34:35], v[24:25], v[24:25]
	global_store_dwordx2 v[50:51], v[36:37], off offset:1024
	v_pk_mov_b32 v[36:37], v[34:35], v[32:33] op_sel:[1,0]
	v_mov_b32_e32 v35, v33
	v_pk_add_f32 v[32:33], v[36:37], v[34:35]
	v_pk_mul_f32 v[34:35], v[18:19], v[18:19]
	v_pk_mul_f32 v[36:37], v[16:17], v[16:17]
	v_pk_add_f32 v[32:33], v[32:33], v[32:33] op_sel:[0,1] op_sel_hi:[1,0]
	v_pk_mov_b32 v[38:39], v[36:37], v[34:35] op_sel:[1,0]
	v_mov_b32_e32 v37, v35
	v_pk_add_f32 v[34:35], v[38:39], v[36:37]
	v_mul_f32_e32 v36, v0, v0
	v_mul_f32_e32 v37, v1, v1
	v_pk_add_f32 v[34:35], v[34:35], v[34:35] op_sel:[0,1] op_sel_hi:[1,0]
	v_mov_b32_e32 v33, v36
	v_mov_b32_e32 v35, v37
	v_pk_add_f32 v[32:33], v[32:33], v[34:35]
	v_mul_f32_e32 v34, v9, v9
	v_mul_f32_e32 v36, v11, v11
	v_mul_f32_e32 v38, v2, v2
	v_mul_f32_e32 v39, v3, v3
	v_pk_fma_f32 v[34:35], v[8:9], v[8:9], v[34:35] op_sel_hi:[1,1,0]
	v_pk_fma_f32 v[36:37], v[10:11], v[10:11], v[36:37] op_sel_hi:[1,1,0]
	v_mov_b32_e32 v35, v38
	v_mov_b32_e32 v37, v39
	v_pk_add_f32 v[34:35], v[34:35], v[36:37]
	v_pk_mul_f32 v[44:45], v[44:45], v[48:49] op_sel_hi:[1,0]
	v_pk_add_f32 v[32:33], v[32:33], v[34:35]
	v_pk_mul_f32 v[46:47], v[46:47], v[48:49] op_sel_hi:[1,0]
	v_add_f32_e32 v32, v32, v33
	ds_bpermute_b32 v33, v90, v32
	v_pk_mul_f32 v[40:41], v[40:41], v[48:49] op_sel_hi:[1,0]
	v_pk_mul_f32 v[42:43], v[42:43], v[48:49] op_sel_hi:[1,0]
	v_pk_mul_f32 v[44:45], v[28:29], v[44:45]
	v_pk_mul_f32 v[46:47], v[30:31], v[46:47]
	s_waitcnt lgkmcnt(0)
	v_add_f32_e32 v32, v32, v33
	ds_bpermute_b32 v33, v89, v32
	v_pk_mul_f32 v[40:41], v[20:21], v[40:41]
	v_pk_mul_f32 v[42:43], v[22:23], v[42:43]
	v_cvt_pk_bf16_f32 v44, v44, v45
	v_cvt_pk_bf16_f32 v45, v46, v47
	s_waitcnt lgkmcnt(0)
	v_add_f32_e32 v32, v32, v33
	ds_bpermute_b32 v33, v81, v32
	v_cvt_pk_bf16_f32 v40, v40, v41
	v_cvt_pk_bf16_f32 v41, v42, v43
	v_lshl_add_u64 v[34:35], v[86:87], 0, s[20:21]
	global_store_dwordx2 v[50:51], v[44:45], off
	s_waitcnt lgkmcnt(0)
	v_add_f32_e32 v32, v32, v33
	ds_bpermute_b32 v33, v91, v32
	global_store_dwordx2 v[50:51], v[40:41], off offset:512
	s_waitcnt lgkmcnt(0)
	v_add_f32_e32 v32, v32, v33
	ds_bpermute_b32 v33, v93, v32
	s_waitcnt lgkmcnt(0)
	v_add_f32_e32 v32, v32, v33
	ds_bpermute_b32 v33, v92, v32
	s_waitcnt lgkmcnt(0)
	v_add_f32_e32 v32, v32, v33
	v_fmamk_f32 v32, v32, 0x3a800000, v230
	v_rsq_f32_e32 v32, v32
	s_nop 0
	v_pk_mul_f32 v[24:25], v[24:25], v[32:33] op_sel_hi:[1,0]
	v_pk_mul_f32 v[26:27], v[26:27], v[32:33] op_sel_hi:[1,0]
	v_pk_mul_f32 v[16:17], v[16:17], v[32:33] op_sel_hi:[1,0]
	v_pk_mul_f32 v[18:19], v[18:19], v[32:33] op_sel_hi:[1,0]
	v_pk_mul_f32 v[8:9], v[8:9], v[32:33] op_sel_hi:[1,0]
	v_pk_mul_f32 v[10:11], v[10:11], v[32:33] op_sel_hi:[1,0]
	v_pk_mul_f32 v[0:1], v[0:1], v[32:33] op_sel_hi:[1,0]
	v_pk_mul_f32 v[2:3], v[2:3], v[32:33] op_sel_hi:[1,0]
	v_pk_mul_f32 v[24:25], v[28:29], v[24:25]
	v_pk_mul_f32 v[26:27], v[30:31], v[26:27]
	v_pk_mul_f32 v[16:17], v[20:21], v[16:17]
	v_pk_mul_f32 v[18:19], v[22:23], v[18:19]
	v_pk_mul_f32 v[8:9], v[12:13], v[8:9]
	v_pk_mul_f32 v[10:11], v[14:15], v[10:11]
	v_pk_mul_f32 v[0:1], v[4:5], v[0:1]
	v_pk_mul_f32 v[2:3], v[6:7], v[2:3]
	v_cvt_pk_bf16_f32 v24, v24, v25
	v_cvt_pk_bf16_f32 v25, v26, v27
	v_cvt_pk_bf16_f32 v16, v16, v17
	v_cvt_pk_bf16_f32 v17, v18, v19
	v_cvt_pk_bf16_f32 v8, v8, v9
	v_cvt_pk_bf16_f32 v9, v10, v11
	v_cvt_pk_bf16_f32 v0, v0, v1
	v_cvt_pk_bf16_f32 v1, v2, v3
	global_store_dwordx2 v[34:35], v[24:25], off
	global_store_dwordx2 v[34:35], v[16:17], off offset:512
	global_store_dwordx2 v[34:35], v[8:9], off offset:1024
	global_store_dwordx2 v[34:35], v[0:1], off offset:1536
	s_cbranch_scc0 .LBB0_826
	v_readlane_b32 s8, v248, 62
	v_readlane_b32 s10, v250, 33
	v_readlane_b32 s58, v247, 1
	v_readlane_b32 s9, v248, 63
	v_readlane_b32 s11, v250, 34
	v_readlane_b32 s59, v247, 2

; __device__ __forceinline__ unsigned pk2(float lo, float hi) { f32x2_t v = {lo, hi}; bf16x2_t b = __builtin_convertvector(v, bf16x2_t); return __builtin_bit_cast(unsigned, b); }
; template <int NR>
; __device__ __forceinline__ void rms_rows_bf16(const float* x, const float* g, bf16* o, int m0, int mstride, int lane) {
;     { size_t z = 0; asm volatile("" : "+s"(z)); g += z; }
;     const f32x4* gr = (const f32x4*)g + lane;
;     f32x4 v[NR][4];
; #pragma unroll
;     for (int k = 0; k < NR; ++k) { const f32x4* xr = (const f32x4*)(x + (size_t)(m0 + k * mstride) * DM) + lane;
; #pragma unroll
;         for (int j = 0; j < 4; ++j) v[k][j] = xr[64 * j]; }
;     f32x4 gg[4];
; #pragma unroll
;     for (int j = 0; j < 4; ++j) gg[j] = gr[64 * j];
; #pragma unroll
;     for (int k = 0; k < NR; ++k) { float s = 0.f;
; #pragma unroll
;         for (int j = 0; j < 4; ++j) s += (v[k][j].x * v[k][j].x + v[k][j].y * v[k][j].y) + (v[k][j].z * v[k][j].z + v[k][j].w * v[k][j].w);
;         const float rs = __builtin_amdgcn_rsqf(wave_sum(s) * (1.f / DM) + 1e-6f);
;         v2u* o8 = (v2u*)(o + (size_t)(m0 + k * mstride) * DM) + lane;
; #pragma unroll
;         for (int j = 0; j < 4; ++j) { v2u w; w.x = pk2(v[k][j].x * rs * gg[j].x, v[k][j].y * rs * gg[j].y); w.y = pk2(v[k][j].z * rs * gg[j].z, v[k][j].w * rs * gg[j].w); o8[64 * j] = w; } }
; }
; __global__ void __launch_bounds__(512) hybrid_fwd(Params p) {
;     ...
;           { int m = gw; for (; m + 3 * NGW < MTOK; m += 4 * NGW) rms_rows_bf16<4>(xo, p.in[15] + l * DM, Hb, m, NGW, C.lane); for (; m < MTOK; m += NGW) rms_rows_bf16<1>(xo, p.in[15] + l * DM, Hb, m, NGW, C.lane); } }
.LBB0_830:
	s_mov_b64 s[20:21], 0
	global_load_dwordx4 v[6:9], v[2:3], off offset:-2048 nt
	global_load_dwordx4 v[10:13], v[2:3], off offset:-1024 nt
	global_load_dwordx4 v[14:17], v[2:3], off nt
	global_load_dwordx4 v[18:21], v[2:3], off offset:1024 nt
	v_lshl_add_u64 v[34:35], s[20:21], 2, v[0:1]
	global_load_dwordx4 v[22:25], v[34:35], off nt
	global_load_dwordx4 v[26:29], v[34:35], off offset:1024 nt
	global_load_dwordx4 v[30:33], v[34:35], off offset:2048 nt
	s_nop 0
	global_load_dwordx4 v[34:37], v[34:35], off offset:3072 nt
	v_and_b32_e32 v38, 64, v228
	v_add_u32_e32 v38, 64, v38
	v_xor_b32_e32 v39, 1, v228
	v_cmp_lt_i32_e32 vcc, v39, v38
	s_add_i32 s44, s44, s76
	v_lshl_add_u64 v[2:3], v[2:3], 0, s[70:71]
	v_cndmask_b32_e32 v46, v228, v39, vcc
	v_xor_b32_e32 v39, 2, v228
	v_cmp_lt_i32_e32 vcc, v39, v38
	s_cmp_lt_i32 s44, 0x8000
	s_waitcnt vmcnt(7)
	v_pk_mul_f32 v[40:41], v[6:7], v[6:7]
	v_cndmask_b32_e32 v47, v228, v39, vcc
	v_xor_b32_e32 v39, 4, v228
	v_cmp_lt_i32_e32 vcc, v39, v38
	s_nop 1
	v_cndmask_b32_e32 v48, v228, v39, vcc
	v_xor_b32_e32 v39, 8, v228
	v_cmp_lt_i32_e32 vcc, v39, v38
	s_nop 1
	v_cndmask_b32_e32 v49, v228, v39, vcc
	v_xor_b32_e32 v39, 16, v228
	v_cmp_lt_i32_e32 vcc, v39, v38
	s_nop 1
	v_cndmask_b32_e32 v50, v228, v39, vcc
	v_xor_b32_e32 v39, 32, v228
	v_cmp_lt_i32_e32 vcc, v39, v38
	s_nop 1
	v_cndmask_b32_e32 v51, v228, v39, vcc
	v_pk_mul_f32 v[38:39], v[8:9], v[8:9]
	s_nop 0
	v_pk_mov_b32 v[42:43], v[40:41], v[38:39] op_sel:[1,0]
	v_mov_b32_e32 v41, v39
	v_pk_add_f32 v[38:39], v[42:43], v[40:41]
	s_waitcnt vmcnt(6)
	v_pk_mul_f32 v[40:41], v[12:13], v[12:13]
	v_pk_mul_f32 v[42:43], v[10:11], v[10:11]
	v_pk_add_f32 v[38:39], v[38:39], v[38:39] op_sel:[0,1] op_sel_hi:[1,0]
	v_pk_mov_b32 v[44:45], v[42:43], v[40:41] op_sel:[1,0]
	v_mov_b32_e32 v43, v41
	v_pk_add_f32 v[40:41], v[44:45], v[42:43]
	s_waitcnt vmcnt(4)
	v_mul_f32_e32 v42, v18, v18
	v_mul_f32_e32 v43, v19, v19
	v_pk_add_f32 v[40:41], v[40:41], v[40:41] op_sel:[0,1] op_sel_hi:[1,0]
	v_mov_b32_e32 v39, v42
	v_mov_b32_e32 v41, v43
	v_pk_add_f32 v[38:39], v[38:39], v[40:41]
	v_mul_f32_e32 v40, v15, v15
	v_mul_f32_e32 v42, v17, v17
	v_mul_f32_e32 v44, v20, v20
	v_mul_f32_e32 v45, v21, v21
	v_pk_fma_f32 v[40:41], v[14:15], v[14:15], v[40:41] op_sel_hi:[1,1,0]
	v_pk_fma_f32 v[42:43], v[16:17], v[16:17], v[42:43] op_sel_hi:[1,1,0]
	v_mov_b32_e32 v41, v44
	v_mov_b32_e32 v43, v45
	v_pk_add_f32 v[40:41], v[40:41], v[42:43]
	v_lshlrev_b32_e32 v42, 2, v49
	v_pk_add_f32 v[38:39], v[38:39], v[40:41]
	v_lshlrev_b32_e32 v40, 2, v47
	v_add_f32_e32 v38, v38, v39
	v_lshlrev_b32_e32 v39, 2, v46
	ds_bpermute_b32 v39, v39, v38
	v_lshlrev_b32_e32 v41, 2, v48
	v_lshlrev_b32_e32 v43, 2, v50
	v_lshlrev_b32_e32 v44, 2, v51
	s_waitcnt lgkmcnt(0)
	v_add_f32_e32 v38, v38, v39
	ds_bpermute_b32 v39, v40, v38
	s_waitcnt lgkmcnt(0)
	v_add_f32_e32 v38, v38, v39
	ds_bpermute_b32 v39, v41, v38
	s_waitcnt lgkmcnt(0)
	v_add_f32_e32 v38, v38, v39
	ds_bpermute_b32 v39, v42, v38
	s_waitcnt lgkmcnt(0)
	v_add_f32_e32 v38, v38, v39
	ds_bpermute_b32 v39, v43, v38
	s_waitcnt lgkmcnt(0)
	v_add_f32_e32 v38, v38, v39
	ds_bpermute_b32 v39, v44, v38
	s_waitcnt lgkmcnt(0)
	v_add_f32_e32 v38, v38, v39
	v_fmamk_f32 v38, v38, 0x3a800000, v230
	v_rsq_f32_e32 v38, v38
	s_nop 0
	v_pk_mul_f32 v[6:7], v[6:7], v[38:39] op_sel_hi:[1,0]
	v_pk_mul_f32 v[8:9], v[8:9], v[38:39] op_sel_hi:[1,0]
	s_waitcnt vmcnt(3)
	v_pk_mul_f32 v[6:7], v[22:23], v[6:7]
	v_pk_mul_f32 v[8:9], v[24:25], v[8:9]
	v_cvt_pk_bf16_f32 v6, v6, v7
	v_cvt_pk_bf16_f32 v7, v8, v9
	global_store_dwordx2 v[4:5], v[6:7], off offset:-1024
	v_pk_mul_f32 v[6:7], v[10:11], v[38:39] op_sel_hi:[1,0]
	v_pk_mul_f32 v[8:9], v[12:13], v[38:39] op_sel_hi:[1,0]
	s_waitcnt vmcnt(3)
	v_pk_mul_f32 v[6:7], v[26:27], v[6:7]
	v_pk_mul_f32 v[8:9], v[28:29], v[8:9]
	v_cvt_pk_bf16_f32 v6, v6, v7
	v_cvt_pk_bf16_f32 v7, v8, v9
	global_store_dwordx2 v[4:5], v[6:7], off offset:-512
	v_pk_mul_f32 v[6:7], v[14:15], v[38:39] op_sel_hi:[1,0]
	v_pk_mul_f32 v[8:9], v[16:17], v[38:39] op_sel_hi:[1,0]
	s_waitcnt vmcnt(3)
	v_pk_mul_f32 v[6:7], v[30:31], v[6:7]
	v_pk_mul_f32 v[8:9], v[32:33], v[8:9]
	v_cvt_pk_bf16_f32 v6, v6, v7
	v_cvt_pk_bf16_f32 v7, v8, v9
	global_store_dwordx2 v[4:5], v[6:7], off
	v_pk_mul_f32 v[6:7], v[18:19], v[38:39] op_sel_hi:[1,0]
	v_pk_mul_f32 v[8:9], v[20:21], v[38:39] op_sel_hi:[1,0]
	s_waitcnt vmcnt(3)
	v_pk_mul_f32 v[6:7], v[34:35], v[6:7]
	v_pk_mul_f32 v[8:9], v[36:37], v[8:9]
	v_cvt_pk_bf16_f32 v6, v6, v7
	v_cvt_pk_bf16_f32 v7, v8, v9
	global_store_dwordx2 v[4:5], v[6:7], off offset:512
	v_lshl_add_u64 v[4:5], v[4:5], 0, s[0:1]
	s_cbranch_scc1 .LBB0_830
	v_readlane_b32 s58, v247, 1
	v_readlane_b32 s59, v247, 2
	v_readlane_b32 s6, v247, 5

; template <int NR>
; __device__ __forceinline__ void rms_rows_f32(float* x, const float* g, int m0, int mstride, int lane) {
;     { size_t z = 0; asm volatile("" : "+s"(z)); g += z; }
;     const f32x4* gr = (const f32x4*)g + lane;
;     f32x4 v[NR][4];
; #pragma unroll
;     for (int k = 0; k < NR; ++k) { const f32x4* xr = (const f32x4*)(x + (size_t)(m0 + k * mstride) * DM) + lane;
; #pragma unroll
;         for (int j = 0; j < 4; ++j) v[k][j] = xr[64 * j]; }
;     f32x4 gg[4];
; #pragma unroll
;     for (int j = 0; j < 4; ++j) gg[j] = gr[64 * j];
; #pragma unroll
;     for (int k = 0; k < NR; ++k) { float s = 0.f;
; #pragma unroll
;         for (int j = 0; j < 4; ++j) s += (v[k][j].x * v[k][j].x + v[k][j].y * v[k][j].y) + (v[k][j].z * v[k][j].z + v[k][j].w * v[k][j].w);
;         const float rs = __builtin_amdgcn_rsqf(wave_sum(s) * (1.f / DM) + 1e-6f);
;         f32x4* xr = (f32x4*)(x + (size_t)(m0 + k * mstride) * DM) + lane;
; #pragma unroll
;         for (int j = 0; j < 4; ++j) xr[64 * j] = v[k][j] * rs * gg[j]; }
; }
; __global__ void __launch_bounds__(512) hybrid_fwd(Params p) {
;     ...
;       { int m = gw; for (; m + 3 * NGW < MTOK; m += 4 * NGW) rms_rows_f32<4>(xo, p.in[18], m, NGW, C.lane); for (; m < MTOK; m += NGW) rms_rows_f32<1>(xo, p.in[18], m, NGW, C.lane); } }
.LBB0_1029:
	s_ashr_i32 s3, s2, 31
	s_lshl_b64 s[6:7], s[2:3], 12
	s_mov_b64 s[4:5], 0
	v_lshl_add_u64 v[92:93], v[82:83], 0, s[6:7]
	global_load_dwordx4 v[76:79], v[92:93], off nt
	global_load_dwordx4 v[72:75], v[92:93], off offset:1024 nt
	global_load_dwordx4 v[60:63], v[92:93], off offset:3072 nt
	global_load_dwordx4 v[64:67], v[92:93], off offset:2048 nt
	s_add_i32 s6, s2, s76
	s_ashr_i32 s7, s6, 31
	s_lshl_b64 s[8:9], s[6:7], 12
	v_lshl_add_u64 v[88:89], v[82:83], 0, s[8:9]
	global_load_dwordx4 v[52:55], v[88:89], off nt
	global_load_dwordx4 v[48:51], v[88:89], off offset:1024 nt
	global_load_dwordx4 v[4:7], v[88:89], off offset:3072 nt
	global_load_dwordx4 v[44:47], v[88:89], off offset:2048 nt
	v_cmp_lt_i32_e32 vcc, v94, v81
	s_add_i32 s8, s16, s2
	s_add_i32 s10, s34, s2
	v_cndmask_b32_e32 v0, v228, v94, vcc
	v_cmp_lt_i32_e32 vcc, v95, v81
	s_ashr_i32 s9, s8, 31
	s_ashr_i32 s11, s10, 31
	v_cndmask_b32_e32 v1, v228, v95, vcc
	v_cmp_lt_i32_e32 vcc, v96, v81
	s_add_i32 s2, s6, s76
	s_lshl_b64 s[6:7], s[8:9], 12
	v_cndmask_b32_e32 v2, v228, v96, vcc
	v_cmp_lt_i32_e32 vcc, v97, v81
	s_lshl_b64 s[8:9], s[10:11], 12
	v_lshl_add_u64 v[56:57], s[4:5], 2, v[84:85]
	v_cndmask_b32_e32 v3, v228, v97, vcc
	v_cmp_lt_i32_e32 vcc, v98, v81
	v_lshlrev_b32_e32 v101, 2, v0
	v_lshlrev_b32_e32 v114, 2, v1
	v_cndmask_b32_e32 v8, v228, v98, vcc
	v_cmp_lt_i32_e32 vcc, v99, v81
	v_lshlrev_b32_e32 v115, 2, v2
	v_lshlrev_b32_e32 v116, 2, v3
	v_cndmask_b32_e32 v9, v228, v99, vcc
	v_lshlrev_b32_e32 v117, 2, v8
	v_lshlrev_b32_e32 v118, 2, v9
	v_lshl_add_u64 v[90:91], v[82:83], 0, s[6:7]
	v_lshl_add_u64 v[86:87], v[82:83], 0, s[8:9]
	global_load_dwordx4 v[16:19], v[56:57], off nt
	global_load_dwordx4 v[12:15], v[56:57], off offset:1024 nt
	global_load_dwordx4 v[8:11], v[56:57], off offset:2048 nt
	global_load_dwordx4 v[0:3], v[56:57], off offset:3072 nt
	global_load_dwordx4 v[40:43], v[90:91], off nt
	global_load_dwordx4 v[36:39], v[90:91], off offset:1024 nt
	global_load_dwordx4 v[32:35], v[90:91], off offset:2048 nt
	global_load_dwordx4 v[28:31], v[90:91], off offset:3072 nt
	global_load_dwordx4 v[24:27], v[86:87], off nt
	global_load_dwordx4 v[20:23], v[86:87], off offset:1024 nt
	s_add_i32 s2, s2, s76
	s_add_i32 s2, s2, s76
	s_add_i32 s3, s34, s2
	s_cmpk_gt_i32 s3, 0x7fff
	s_waitcnt vmcnt(17)
	v_pk_mul_f32 v[56:57], v[78:79], v[78:79]
	v_pk_mul_f32 v[58:59], v[76:77], v[76:77]
	s_waitcnt vmcnt(16)
	v_pk_mul_f32 v[68:69], v[74:75], v[74:75]
	v_pk_mul_f32 v[70:71], v[72:73], v[72:73]
	v_pk_mov_b32 v[106:107], v[58:59], v[56:57] op_sel:[1,0]
	v_mov_b32_e32 v59, v57
	v_pk_mov_b32 v[56:57], v[70:71], v[68:69] op_sel:[1,0]
	v_mov_b32_e32 v71, v69
	s_waitcnt vmcnt(14)
	v_mul_f32_e32 v102, v65, v65
	v_mul_f32_e32 v104, v67, v67
	v_pk_add_f32 v[58:59], v[106:107], v[58:59]
	v_pk_add_f32 v[56:57], v[56:57], v[70:71]
	v_mul_f32_e32 v119, v60, v60
	v_mul_f32_e32 v120, v61, v61
	v_mul_f32_e32 v121, v62, v62
	v_mul_f32_e32 v122, v63, v63
	v_pk_fma_f32 v[68:69], v[64:65], v[64:65], v[102:103] op_sel_hi:[1,1,0]
	v_pk_fma_f32 v[102:103], v[66:67], v[66:67], v[104:105] op_sel_hi:[1,1,0]
	v_pk_add_f32 v[58:59], v[58:59], v[58:59] op_sel:[0,1] op_sel_hi:[1,0]
	v_pk_add_f32 v[56:57], v[56:57], v[56:57] op_sel:[0,1] op_sel_hi:[1,0]
	v_mov_b32_e32 v69, v121
	v_mov_b32_e32 v103, v122
	v_mov_b32_e32 v59, v119
	v_mov_b32_e32 v57, v120
	v_pk_add_f32 v[68:69], v[68:69], v[102:103]
	v_pk_add_f32 v[56:57], v[58:59], v[56:57]
	s_waitcnt vmcnt(13)
	v_pk_mul_f32 v[104:105], v[54:55], v[54:55]
	v_pk_add_f32 v[56:57], v[56:57], v[68:69]
	v_pk_mul_f32 v[108:109], v[52:53], v[52:53]
	v_add_f32_e32 v57, v56, v57
	ds_bpermute_b32 v58, v101, v57
	v_pk_mov_b32 v[68:69], v[108:109], v[104:105] op_sel:[1,0]
	v_mov_b32_e32 v109, v105
	s_waitcnt vmcnt(10)
	v_mul_f32_e32 v56, v45, v45
	v_mul_f32_e32 v103, v6, v6
	s_waitcnt lgkmcnt(0)
	v_add_f32_e32 v57, v57, v58
	ds_bpermute_b32 v59, v114, v57
	v_pk_mul_f32 v[110:111], v[50:51], v[50:51]
	v_pk_mul_f32 v[112:113], v[48:49], v[48:49]
	v_mul_f32_e32 v102, v5, v5
	v_pk_mov_b32 v[70:71], v[112:113], v[110:111] op_sel:[1,0]
	s_waitcnt lgkmcnt(0)
	v_add_f32_e32 v104, v57, v59
	ds_bpermute_b32 v105, v115, v104
	v_pk_fma_f32 v[56:57], v[44:45], v[44:45], v[56:57] op_sel_hi:[1,1,0]
	v_mov_b32_e32 v113, v111
	v_mov_b32_e32 v57, v103
	v_pk_add_f32 v[70:71], v[70:71], v[112:113]
	s_waitcnt lgkmcnt(0)
	v_add_f32_e32 v104, v104, v105
	ds_bpermute_b32 v105, v116, v104
	v_pk_add_f32 v[70:71], v[70:71], v[70:71] op_sel:[0,1] op_sel_hi:[1,0]
	v_mul_f32_e32 v58, v47, v47
	v_mov_b32_e32 v71, v102
	v_pk_add_f32 v[68:69], v[68:69], v[108:109]
	s_waitcnt lgkmcnt(0)
	v_add_f32_e32 v103, v104, v105
	ds_bpermute_b32 v104, v117, v103
	v_mul_f32_e32 v123, v4, v4
	v_mul_f32_e32 v106, v7, v7
	v_pk_fma_f32 v[58:59], v[46:47], v[46:47], v[58:59] op_sel_hi:[1,1,0]
	v_pk_add_f32 v[68:69], v[68:69], v[68:69] op_sel:[0,1] op_sel_hi:[1,0]
	s_waitcnt lgkmcnt(0)
	v_add_f32_e32 v102, v103, v104
	ds_bpermute_b32 v103, v118, v102
	v_mov_b32_e32 v59, v106
	v_mov_b32_e32 v69, v123
	v_pk_add_f32 v[56:57], v[56:57], v[58:59]
	v_pk_add_f32 v[58:59], v[68:69], v[70:71]
	s_nop 0
	v_pk_add_f32 v[56:57], v[58:59], v[56:57]
	s_nop 0
	v_add_f32_e32 v104, v56, v57
	s_waitcnt lgkmcnt(0)
	v_add_f32_e32 v56, v102, v103
	v_fmamk_f32 v56, v56, 0x3a800000, v100
	v_rsq_f32_e32 v102, v56
	global_load_dwordx4 v[68:71], v[86:87], off offset:2048 nt
	global_load_dwordx4 v[56:59], v[86:87], off offset:3072 nt
	ds_bpermute_b32 v105, v101, v104
	s_waitcnt lgkmcnt(0)
	v_add_f32_e32 v103, v104, v105
	ds_bpermute_b32 v104, v114, v103
	v_pk_mul_f32 v[76:77], v[76:77], v[102:103] op_sel_hi:[1,0]
	v_pk_mul_f32 v[78:79], v[78:79], v[102:103] op_sel_hi:[1,0]
	s_waitcnt vmcnt(11)
; template <int NR>
; __device__ __forceinline__ void rms_rows_f32(float* x, const float* g, int m0, int mstride, int lane) {
;     { size_t z = 0; asm volatile("" : "+s"(z)); g += z; }
;     const f32x4* gr = (const f32x4*)g + lane;
;     f32x4 v[NR][4];
; #pragma unroll
;     for (int k = 0; k < NR; ++k) { const f32x4* xr = (const f32x4*)(x + (size_t)(m0 + k * mstride) * DM) + lane;
; #pragma unroll
;         for (int j = 0; j < 4; ++j) v[k][j] = xr[64 * j]; }
;     f32x4 gg[4];
; #pragma unroll
;     for (int j = 0; j < 4; ++j) gg[j] = gr[64 * j];
; #pragma unroll
;     for (int k = 0; k < NR; ++k) { float s = 0.f;
; #pragma unroll
;         for (int j = 0; j < 4; ++j) s += (v[k][j].x * v[k][j].x + v[k][j].y * v[k][j].y) + (v[k][j].z * v[k][j].z + v[k][j].w * v[k][j].w);
;         const float rs = __builtin_amdgcn_rsqf(wave_sum(s) * (1.f / DM) + 1e-6f);
;         f32x4* xr = (f32x4*)(x + (size_t)(m0 + k * mstride) * DM) + lane;
; #pragma unroll
;         for (int j = 0; j < 4; ++j) xr[64 * j] = v[k][j] * rs * gg[j]; }
; }
	v_pk_mul_f32 v[76:77], v[16:17], v[76:77]
	v_pk_mul_f32 v[78:79], v[18:19], v[78:79]
	global_store_dwordx4 v[92:93], v[76:79], off
	v_pk_mul_f32 v[72:73], v[72:73], v[102:103] op_sel_hi:[1,0]
	v_pk_mul_f32 v[74:75], v[74:75], v[102:103] op_sel_hi:[1,0]
	s_waitcnt lgkmcnt(0)
	v_add_f32_e32 v76, v103, v104
	ds_bpermute_b32 v77, v115, v76
	s_waitcnt vmcnt(11)
	v_pk_mul_f32 v[74:75], v[14:15], v[74:75]
	v_pk_mul_f32 v[72:73], v[12:13], v[72:73]
	global_store_dwordx4 v[92:93], v[72:75], off offset:1024
	v_pk_mul_f32 v[64:65], v[64:65], v[102:103] op_sel_hi:[1,0]
	v_pk_mul_f32 v[66:67], v[66:67], v[102:103] op_sel_hi:[1,0]
	s_waitcnt lgkmcnt(0)
	v_add_f32_e32 v72, v76, v77
	ds_bpermute_b32 v73, v116, v72
	s_waitcnt vmcnt(11)
	v_pk_mul_f32 v[66:67], v[10:11], v[66:67]
	v_pk_mul_f32 v[64:65], v[8:9], v[64:65]
	global_store_dwordx4 v[92:93], v[64:67], off offset:2048
	v_pk_mul_f32 v[60:61], v[60:61], v[102:103] op_sel_hi:[1,0]
	v_pk_mul_f32 v[62:63], v[62:63], v[102:103] op_sel_hi:[1,0]
	s_waitcnt lgkmcnt(0)
	v_add_f32_e32 v64, v72, v73
	ds_bpermute_b32 v65, v117, v64
	s_waitcnt vmcnt(10)
	v_pk_mul_f32 v[66:67], v[40:41], v[40:41]
	v_pk_mul_f32 v[62:63], v[2:3], v[62:63]
	v_pk_mul_f32 v[60:61], v[0:1], v[60:61]
	global_store_dwordx4 v[92:93], v[60:63], off offset:3072
	s_waitcnt lgkmcnt(0)
	v_add_f32_e32 v76, v64, v65
	v_pk_mul_f32 v[64:65], v[42:43], v[42:43]
	ds_bpermute_b32 v77, v118, v76
	v_pk_mov_b32 v[72:73], v[66:67], v[64:65] op_sel:[1,0]
	v_mov_b32_e32 v67, v65
	v_pk_add_f32 v[64:65], v[72:73], v[66:67]
	s_waitcnt vmcnt(10)
	v_pk_mul_f32 v[66:67], v[38:39], v[38:39]
	v_pk_mul_f32 v[72:73], v[36:37], v[36:37]
	v_pk_add_f32 v[64:65], v[64:65], v[64:65] op_sel:[0,1] op_sel_hi:[1,0]
	v_pk_mov_b32 v[74:75], v[72:73], v[66:67] op_sel:[1,0]
	v_mov_b32_e32 v73, v67
	v_pk_add_f32 v[66:67], v[74:75], v[72:73]
	s_waitcnt vmcnt(8)
	v_mul_f32_e32 v72, v28, v28
	v_mul_f32_e32 v73, v29, v29
	v_pk_add_f32 v[66:67], v[66:67], v[66:67] op_sel:[0,1] op_sel_hi:[1,0]
	v_mov_b32_e32 v65, v72
	v_mov_b32_e32 v67, v73
	v_pk_add_f32 v[64:65], v[64:65], v[66:67]
	v_mul_f32_e32 v66, v33, v33
	v_mul_f32_e32 v72, v35, v35
	v_mul_f32_e32 v74, v30, v30
	v_mul_f32_e32 v75, v31, v31
	v_pk_fma_f32 v[66:67], v[32:33], v[32:33], v[66:67] op_sel_hi:[1,1,0]
	v_pk_fma_f32 v[72:73], v[34:35], v[34:35], v[72:73] op_sel_hi:[1,1,0]
	v_mov_b32_e32 v67, v74
	v_mov_b32_e32 v73, v75
	v_pk_add_f32 v[66:67], v[66:67], v[72:73]
	s_nop 0
	v_pk_add_f32 v[64:65], v[64:65], v[66:67]
	s_nop 0
	v_add_f32_e32 v65, v64, v65
	ds_bpermute_b32 v66, v101, v65
	s_waitcnt lgkmcnt(1)
	v_add_f32_e32 v64, v76, v77
	v_fmamk_f32 v64, v64, 0x3a800000, v100
	v_rsq_f32_e32 v64, v64
	s_waitcnt lgkmcnt(0)
	v_add_f32_e32 v60, v65, v66
	ds_bpermute_b32 v61, v114, v60
	v_pk_mul_f32 v[52:53], v[52:53], v[64:65] op_sel_hi:[1,0]
	v_pk_mul_f32 v[54:55], v[54:55], v[64:65] op_sel_hi:[1,0]
	v_pk_mul_f32 v[52:53], v[16:17], v[52:53]
	v_pk_mul_f32 v[54:55], v[18:19], v[54:55]
	s_waitcnt lgkmcnt(0)
	v_add_f32_e32 v60, v60, v61
	ds_bpermute_b32 v61, v115, v60
	global_store_dwordx4 v[88:89], v[52:55], off
	v_pk_mul_f32 v[48:49], v[48:49], v[64:65] op_sel_hi:[1,0]
	v_pk_mul_f32 v[50:51], v[50:51], v[64:65] op_sel_hi:[1,0]
	v_pk_mul_f32 v[48:49], v[12:13], v[48:49]
	s_waitcnt lgkmcnt(0)
	v_add_f32_e32 v52, v60, v61
	ds_bpermute_b32 v53, v116, v52
	v_pk_mul_f32 v[50:51], v[14:15], v[50:51]
	global_store_dwordx4 v[88:89], v[48:51], off offset:1024
	v_pk_mul_f32 v[44:45], v[44:45], v[64:65] op_sel_hi:[1,0]
	v_pk_mul_f32 v[46:47], v[46:47], v[64:65] op_sel_hi:[1,0]
	s_waitcnt lgkmcnt(0)
	v_add_f32_e32 v48, v52, v53
	ds_bpermute_b32 v49, v117, v48
	v_pk_mul_f32 v[46:47], v[10:11], v[46:47]
	v_pk_mul_f32 v[44:45], v[8:9], v[44:45]
	global_store_dwordx4 v[88:89], v[44:47], off offset:2048
	v_pk_mul_f32 v[4:5], v[4:5], v[64:65] op_sel_hi:[1,0]
	s_waitcnt lgkmcnt(0)
	v_add_f32_e32 v52, v48, v49
	s_waitcnt vmcnt(10)
; template <int NR>
; __device__ __forceinline__ void rms_rows_f32(float* x, const float* g, int m0, int mstride, int lane) {
;     { size_t z = 0; asm volatile("" : "+s"(z)); g += z; }
;     const f32x4* gr = (const f32x4*)g + lane;
;     f32x4 v[NR][4];
; #pragma unroll
;     for (int k = 0; k < NR; ++k) { const f32x4* xr = (const f32x4*)(x + (size_t)(m0 + k * mstride) * DM) + lane;
; #pragma unroll
;         for (int j = 0; j < 4; ++j) v[k][j] = xr[64 * j]; }
;     f32x4 gg[4];
; #pragma unroll
;     for (int j = 0; j < 4; ++j) gg[j] = gr[64 * j];
; #pragma unroll
;     for (int k = 0; k < NR; ++k) { float s = 0.f;
; #pragma unroll
;         for (int j = 0; j < 4; ++j) s += (v[k][j].x * v[k][j].x + v[k][j].y * v[k][j].y) + (v[k][j].z * v[k][j].z + v[k][j].w * v[k][j].w);
;         const float rs = __builtin_amdgcn_rsqf(wave_sum(s) * (1.f / DM) + 1e-6f);
;         f32x4* xr = (f32x4*)(x + (size_t)(m0 + k * mstride) * DM) + lane;
; #pragma unroll
;         for (int j = 0; j < 4; ++j) xr[64 * j] = v[k][j] * rs * gg[j]; }
; }
	v_pk_mul_f32 v[44:45], v[26:27], v[26:27]
	v_pk_mul_f32 v[46:47], v[24:25], v[24:25]
	ds_bpermute_b32 v53, v118, v52
	v_pk_mov_b32 v[48:49], v[46:47], v[44:45] op_sel:[1,0]
	v_mov_b32_e32 v47, v45
	v_pk_add_f32 v[44:45], v[48:49], v[46:47]
	s_waitcnt vmcnt(9)
	v_pk_mul_f32 v[46:47], v[22:23], v[22:23]
	v_pk_mul_f32 v[48:49], v[20:21], v[20:21]
	v_pk_add_f32 v[44:45], v[44:45], v[44:45] op_sel:[0,1] op_sel_hi:[1,0]
	v_pk_mov_b32 v[50:51], v[48:49], v[46:47] op_sel:[1,0]
	v_mov_b32_e32 v49, v47
	v_pk_add_f32 v[46:47], v[50:51], v[48:49]
	s_waitcnt vmcnt(7)
	v_mul_f32_e32 v48, v56, v56
	v_mul_f32_e32 v49, v57, v57
	v_pk_add_f32 v[46:47], v[46:47], v[46:47] op_sel:[0,1] op_sel_hi:[1,0]
	v_mov_b32_e32 v45, v48
	v_mov_b32_e32 v47, v49
	v_pk_add_f32 v[44:45], v[44:45], v[46:47]
	v_mul_f32_e32 v46, v69, v69
	v_mul_f32_e32 v48, v71, v71
	v_mul_f32_e32 v50, v58, v58
	v_mul_f32_e32 v51, v59, v59
	v_pk_fma_f32 v[46:47], v[68:69], v[68:69], v[46:47] op_sel_hi:[1,1,0]
	v_pk_fma_f32 v[48:49], v[70:71], v[70:71], v[48:49] op_sel_hi:[1,1,0]
	v_mov_b32_e32 v47, v50
	v_mov_b32_e32 v49, v51
	v_pk_add_f32 v[46:47], v[46:47], v[48:49]
	v_pk_mul_f32 v[6:7], v[6:7], v[64:65] op_sel_hi:[1,0]
	v_pk_add_f32 v[44:45], v[44:45], v[46:47]
	v_pk_mul_f32 v[6:7], v[2:3], v[6:7]
	v_add_f32_e32 v45, v44, v45
	ds_bpermute_b32 v46, v101, v45
	s_waitcnt lgkmcnt(1)
	v_add_f32_e32 v44, v52, v53
	v_fmamk_f32 v44, v44, 0x3a800000, v100
	v_rsq_f32_e32 v44, v44
	v_pk_mul_f32 v[4:5], v[0:1], v[4:5]
	s_waitcnt lgkmcnt(0)
	v_add_f32_e32 v45, v45, v46
	ds_bpermute_b32 v46, v114, v45
	global_store_dwordx4 v[88:89], v[4:7], off offset:3072
	s_nop 1
	v_pk_mul_f32 v[4:5], v[40:41], v[44:45] op_sel_hi:[1,0]
	s_waitcnt lgkmcnt(0)
	v_add_f32_e32 v40, v45, v46
	ds_bpermute_b32 v41, v115, v40
	v_pk_mul_f32 v[6:7], v[42:43], v[44:45] op_sel_hi:[1,0]
	v_pk_mul_f32 v[4:5], v[16:17], v[4:5]
	v_pk_mul_f32 v[6:7], v[18:19], v[6:7]
	global_store_dwordx4 v[90:91], v[4:7], off
	s_waitcnt lgkmcnt(0)
	v_add_f32_e32 v40, v40, v41
	ds_bpermute_b32 v41, v116, v40
	v_pk_mul_f32 v[4:5], v[36:37], v[44:45] op_sel_hi:[1,0]
	v_pk_mul_f32 v[6:7], v[38:39], v[44:45] op_sel_hi:[1,0]
	v_pk_mul_f32 v[4:5], v[12:13], v[4:5]
	v_pk_mul_f32 v[6:7], v[14:15], v[6:7]
	s_waitcnt lgkmcnt(0)
	v_add_f32_e32 v36, v40, v41
	ds_bpermute_b32 v37, v117, v36
	global_store_dwordx4 v[90:91], v[4:7], off offset:1024
	s_nop 1
	v_pk_mul_f32 v[4:5], v[32:33], v[44:45] op_sel_hi:[1,0]
	s_waitcnt lgkmcnt(0)
	v_add_f32_e32 v32, v36, v37
	ds_bpermute_b32 v33, v118, v32
	v_pk_mul_f32 v[6:7], v[34:35], v[44:45] op_sel_hi:[1,0]
	v_pk_mul_f32 v[4:5], v[8:9], v[4:5]
	v_pk_mul_f32 v[6:7], v[10:11], v[6:7]
	global_store_dwordx4 v[90:91], v[4:7], off offset:2048
	s_nop 1
	v_pk_mul_f32 v[4:5], v[28:29], v[44:45] op_sel_hi:[1,0]
	s_waitcnt lgkmcnt(0)
	v_add_f32_e32 v28, v32, v33
	v_fmamk_f32 v28, v28, 0x3a800000, v100
	v_rsq_f32_e32 v28, v28
	v_pk_mul_f32 v[6:7], v[30:31], v[44:45] op_sel_hi:[1,0]
	v_pk_mul_f32 v[4:5], v[0:1], v[4:5]
	v_pk_mul_f32 v[6:7], v[2:3], v[6:7]
	global_store_dwordx4 v[90:91], v[4:7], off offset:3072
	s_nop 1
	v_pk_mul_f32 v[4:5], v[24:25], v[28:29] op_sel_hi:[1,0]
	v_pk_mul_f32 v[6:7], v[26:27], v[28:29] op_sel_hi:[1,0]
	v_pk_mul_f32 v[4:5], v[16:17], v[4:5]
	v_pk_mul_f32 v[6:7], v[18:19], v[6:7]
	global_store_dwordx4 v[86:87], v[4:7], off
	s_nop 1
	v_pk_mul_f32 v[4:5], v[20:21], v[28:29] op_sel_hi:[1,0]
	v_pk_mul_f32 v[6:7], v[22:23], v[28:29] op_sel_hi:[1,0]
	v_pk_mul_f32 v[4:5], v[12:13], v[4:5]
	v_pk_mul_f32 v[6:7], v[14:15], v[6:7]
	global_store_dwordx4 v[86:87], v[4:7], off offset:1024
	s_nop 1
	v_pk_mul_f32 v[4:5], v[68:69], v[28:29] op_sel_hi:[1,0]
	v_pk_mul_f32 v[6:7], v[70:71], v[28:29] op_sel_hi:[1,0]
	v_pk_mul_f32 v[4:5], v[8:9], v[4:5]
	v_pk_mul_f32 v[6:7], v[10:11], v[6:7]
	global_store_dwordx4 v[86:87], v[4:7], off offset:2048
	s_nop 1
	v_pk_mul_f32 v[4:5], v[56:57], v[28:29] op_sel_hi:[1,0]
	v_pk_mul_f32 v[6:7], v[58:59], v[28:29] op_sel_hi:[1,0]
	v_pk_mul_f32 v[0:1], v[0:1], v[4:5]
	v_pk_mul_f32 v[2:3], v[2:3], v[6:7]
	global_store_dwordx4 v[86:87], v[0:3], off offset:3072
	s_cbranch_scc0 .LBB0_1029

; template <int NR>
; __device__ __forceinline__ void rms_rows_f32(float* x, const float* g, int m0, int mstride, int lane) {
;     { size_t z = 0; asm volatile("" : "+s"(z)); g += z; }
;     const f32x4* gr = (const f32x4*)g + lane;
;     f32x4 v[NR][4];
; #pragma unroll
;     for (int k = 0; k < NR; ++k) { const f32x4* xr = (const f32x4*)(x + (size_t)(m0 + k * mstride) * DM) + lane;
; #pragma unroll
;         for (int j = 0; j < 4; ++j) v[k][j] = xr[64 * j]; }
;     f32x4 gg[4];
; #pragma unroll
;     for (int j = 0; j < 4; ++j) gg[j] = gr[64 * j];
; #pragma unroll
;     for (int k = 0; k < NR; ++k) { float s = 0.f;
; #pragma unroll
;         for (int j = 0; j < 4; ++j) s += (v[k][j].x * v[k][j].x + v[k][j].y * v[k][j].y) + (v[k][j].z * v[k][j].z + v[k][j].w * v[k][j].w);
;         const float rs = __builtin_amdgcn_rsqf(wave_sum(s) * (1.f / DM) + 1e-6f);
;         f32x4* xr = (f32x4*)(x + (size_t)(m0 + k * mstride) * DM) + lane;
; #pragma unroll
;         for (int j = 0; j < 4; ++j) xr[64 * j] = v[k][j] * rs * gg[j]; }
; }
; __global__ void __launch_bounds__(512) hybrid_fwd(Params p) {
;     ...
;       { int m = gw; for (; m + 3 * NGW < MTOK; m += 4 * NGW) rms_rows_f32<4>(xo, p.in[18], m, NGW, C.lane); for (; m < MTOK; m += NGW) rms_rows_f32<1>(xo, p.in[18], m, NGW, C.lane); } }
.LBB0_1032:
	s_mov_b64 s[0:1], 0
	global_load_dwordx4 v[12:15], v[2:3], off offset:-3072 nt
	global_load_dwordx4 v[16:19], v[2:3], off offset:-2048 nt
	global_load_dwordx4 v[20:23], v[2:3], off nt
	global_load_dwordx4 v[24:27], v[2:3], off offset:-1024 nt
	v_cmp_lt_i32_e32 vcc, v5, v4
	v_lshl_add_u64 v[44:45], s[0:1], 2, v[0:1]
	s_add_i32 s2, s2, s76
	v_cndmask_b32_e32 v28, v228, v5, vcc
	v_lshlrev_b32_e32 v55, 2, v28
	global_load_dwordx4 v[28:31], v[44:45], off nt
	global_load_dwordx4 v[32:35], v[44:45], off offset:1024 nt
	global_load_dwordx4 v[36:39], v[44:45], off offset:2048 nt
	global_load_dwordx4 v[40:43], v[44:45], off offset:3072 nt
	v_cmp_lt_i32_e32 vcc, v6, v4
	s_cmp_lt_i32 s2, 0x8000
	s_waitcnt vmcnt(7)
	v_pk_mul_f32 v[44:45], v[14:15], v[14:15]
	v_pk_mul_f32 v[46:47], v[12:13], v[12:13]
	s_waitcnt vmcnt(6)
	v_pk_mul_f32 v[48:49], v[18:19], v[18:19]
	v_pk_mul_f32 v[50:51], v[16:17], v[16:17]
	v_pk_mov_b32 v[56:57], v[46:47], v[44:45] op_sel:[1,0]
	v_mov_b32_e32 v47, v45
	v_pk_mov_b32 v[44:45], v[50:51], v[48:49] op_sel:[1,0]
	v_mov_b32_e32 v51, v49
	s_waitcnt vmcnt(4)
	v_mul_f32_e32 v52, v25, v25
	v_mul_f32_e32 v54, v27, v27
	v_pk_add_f32 v[46:47], v[56:57], v[46:47]
	v_pk_add_f32 v[44:45], v[44:45], v[50:51]
	v_mul_f32_e32 v58, v20, v20
	v_mul_f32_e32 v59, v21, v21
	v_mul_f32_e32 v60, v22, v22
	v_mul_f32_e32 v61, v23, v23
	v_pk_fma_f32 v[48:49], v[24:25], v[24:25], v[52:53] op_sel_hi:[1,1,0]
	v_pk_fma_f32 v[52:53], v[26:27], v[26:27], v[54:55] op_sel_hi:[1,1,0]
	v_pk_add_f32 v[46:47], v[46:47], v[46:47] op_sel:[0,1] op_sel_hi:[1,0]
	v_pk_add_f32 v[44:45], v[44:45], v[44:45] op_sel:[0,1] op_sel_hi:[1,0]
	v_mov_b32_e32 v49, v60
	v_mov_b32_e32 v53, v61
	v_mov_b32_e32 v47, v58
	v_mov_b32_e32 v45, v59
	v_pk_add_f32 v[48:49], v[48:49], v[52:53]
	v_pk_add_f32 v[44:45], v[46:47], v[44:45]
	v_cndmask_b32_e32 v46, v228, v6, vcc
	v_pk_add_f32 v[44:45], v[44:45], v[48:49]
	v_lshlrev_b32_e32 v46, 2, v46
	v_add_f32_e32 v44, v44, v45
	ds_bpermute_b32 v45, v55, v44
	v_cmp_lt_i32_e32 vcc, v7, v4
	s_waitcnt lgkmcnt(0)
	v_add_f32_e32 v44, v44, v45
	ds_bpermute_b32 v45, v46, v44
	v_cndmask_b32_e32 v46, v228, v7, vcc
	v_lshlrev_b32_e32 v46, 2, v46
	v_cmp_lt_i32_e32 vcc, v8, v4
	s_waitcnt lgkmcnt(0)
	v_add_f32_e32 v44, v44, v45
	ds_bpermute_b32 v45, v46, v44
	v_cndmask_b32_e32 v46, v228, v8, vcc
	v_lshlrev_b32_e32 v46, 2, v46
	v_cmp_lt_i32_e32 vcc, v9, v4
	s_waitcnt lgkmcnt(0)
	v_add_f32_e32 v44, v44, v45
	ds_bpermute_b32 v45, v46, v44
	v_cndmask_b32_e32 v46, v228, v9, vcc
	v_lshlrev_b32_e32 v46, 2, v46
	v_cmp_lt_i32_e32 vcc, v10, v4
	s_waitcnt lgkmcnt(0)
	v_add_f32_e32 v44, v44, v45
	ds_bpermute_b32 v45, v46, v44
	v_cndmask_b32_e32 v46, v228, v10, vcc
	v_lshlrev_b32_e32 v46, 2, v46
	s_waitcnt lgkmcnt(0)
	v_add_f32_e32 v44, v44, v45
	ds_bpermute_b32 v45, v46, v44
	s_waitcnt lgkmcnt(0)
	v_add_f32_e32 v44, v44, v45
	v_fmamk_f32 v44, v44, 0x3a800000, v11
	v_rsq_f32_e32 v44, v44
	s_nop 0
	v_pk_mul_f32 v[12:13], v[12:13], v[44:45] op_sel_hi:[1,0]
	v_pk_mul_f32 v[14:15], v[14:15], v[44:45] op_sel_hi:[1,0]
	v_pk_mul_f32 v[16:17], v[16:17], v[44:45] op_sel_hi:[1,0]
	v_pk_mul_f32 v[18:19], v[18:19], v[44:45] op_sel_hi:[1,0]
	v_pk_mul_f32 v[24:25], v[24:25], v[44:45] op_sel_hi:[1,0]
	v_pk_mul_f32 v[26:27], v[26:27], v[44:45] op_sel_hi:[1,0]
	v_pk_mul_f32 v[46:47], v[20:21], v[44:45] op_sel_hi:[1,0]
	v_pk_mul_f32 v[44:45], v[22:23], v[44:45] op_sel_hi:[1,0]
	s_waitcnt vmcnt(3)
	v_pk_mul_f32 v[14:15], v[30:31], v[14:15]
	v_pk_mul_f32 v[12:13], v[28:29], v[12:13]
	s_waitcnt vmcnt(2)
	v_pk_mul_f32 v[18:19], v[34:35], v[18:19]
	v_pk_mul_f32 v[16:17], v[32:33], v[16:17]
	s_waitcnt vmcnt(1)
	v_pk_mul_f32 v[22:23], v[38:39], v[26:27]
	v_pk_mul_f32 v[20:21], v[36:37], v[24:25]
	s_waitcnt vmcnt(0)
	v_pk_mul_f32 v[26:27], v[42:43], v[44:45]
	v_pk_mul_f32 v[24:25], v[40:41], v[46:47]
	global_store_dwordx4 v[2:3], v[12:15], off offset:-3072
	global_store_dwordx4 v[2:3], v[16:19], off offset:-2048
	global_store_dwordx4 v[2:3], v[20:23], off offset:-1024
	global_store_dwordx4 v[2:3], v[24:27], off
	v_lshl_add_u64 v[2:3], v[2:3], 0, s[70:71]
	s_cbranch_scc1 .LBB0_1032
